# GEMM K-loops: removed redundant post-barrier lgkmcnt(0) waits (stacked)
# baseline (speedup 1.0000x reference)
; #define PG8_STAGE(bufoff, gbase, voff) do { _Pragma("unroll") for (int _i = 0; _i < 2; ++_i) \
;         __builtin_amdgcn_global_load_lds((const unsigned*)((const char*)(gbase) + (voff)[_i]), (PG8_LAS unsigned*)(lds + (bufoff) + ldsw + _i * 8192), 16, 0, 0); } while (0)
; #define PG8_LDA(dst, b, h) do { _Pragma("unroll") for (int m = 0; m < 4; ++m) _Pragma("unroll") for (int k = 0; k < 2; ++k) dst[m][k] = *(const PG8_LAS bf16x8*)(lds + PG8_SA(b, h) + aoff + m * 2048 + k * 1024); } while (0)
; #define PG8_LDB(dst, b, h) do { _Pragma("unroll") for (int n = 0; n < 2; ++n) _Pragma("unroll") for (int k = 0; k < 2; ++k) dst[n][k] = *(const PG8_LAS bf16x8*)(lds + PG8_SB(b, h) + boff + n * 2048 + k * 1024); } while (0)
; #define PG8_MMA(ai, bj, At, Bt) do { __builtin_amdgcn_s_setprio(1); _Pragma("unroll") for (int m = 0; m < 4; ++m) _Pragma("unroll") for (int n = 0; n < 2; ++n) _Pragma("unroll") for (int k = 0; k < 2; ++k) \
;         acc[ai][bj][m][n] = __builtin_amdgcn_mfma_f32_16x16x32_bf16(Bt[n][k], At[m][k], acc[ai][bj][m][n], 0, 0, 0); __builtin_amdgcn_s_setprio(0); } while (0)
; #define PG8_WAIT_V(n) asm volatile("s_waitcnt vmcnt(" #n ")" ::: "memory")
; #define PG8_BAR __builtin_amdgcn_s_barrier()
; template <class Epi, class Sched, bool ALIGN_EPI = false, bool SP2 = false>
; __device__ __forceinline__ void gemm_phase(PG8_LAS unsigned char* lds, const Gemm g, const Sched& S, const Epi& E) {
;     ...
;         for (int t = 0; t < nt; t += 2) {
;             const bool last = (t == nt - 2);
;             const char* a1 = cA + (size_t)(t + 1) * kstep;
;             const char* a2 = last ? nA : cA + (size_t)(t + 2) * kstep; const char* b2 = last ? nB : cB + (size_t)(t + 2) * kstep;
;             const char* a3 = a2 + kstep; const char* b3 = b2 + kstep;
;             if (last && has_next) S.a_ready(nxt);
;             if constexpr (SP2) {
;             PG8_LDB(B0, 0, 0); PG8_LDB(B1, 0, 1); PG8_SCHED; PG8_LDA(At, 0, 0); PG8_STAGE(PG8_SA(1, 1), a1 + hstep, voffA);
;             PG8_WAIT_V(8); PG8_WAIT_L(0); PG8_BAR; PG8_MMA(0, 0, At, B0); PG8_MMA(0, 1, At, B1); PG8_BAR; PG8_SCHED;
;             PG8_LDA(At, 0, 1); PG8_STAGE(PG8_SB(0, 0), b2, voffB); PG8_STAGE(PG8_SB(0, 1), b2 + hstep, voffB); PG8_STAGE(PG8_SA(0, 0), a2, voffA);
;             PG8_WAIT_V(8); PG8_WAIT_L(0); PG8_BAR; PG8_MMA(1, 0, At, B0); PG8_MMA(1, 1, At, B1); PG8_BAR; PG8_SCHED;
.LBB0_164:
	s_add_u32 s58, s72, 0xfffc0080
	s_addc_u32 s59, s73, -1
	s_add_i32 s84, 0, 0x10000
	s_cmp_eq_u32 s94, 12
	s_cselect_b32 s65, s36, s59
	s_cselect_b32 s64, s37, s58
	v_add_u32_e32 v140, s84, v146
	s_cselect_b32 s59, s51, s93
	s_cselect_b32 s58, s53, s92
	s_add_i32 s96, 0, 0x14000
	ds_read_b128 v[142:145], v140
	ds_read_b128 v[150:153], v140 offset:1024
	ds_read_b128 v[154:157], v140 offset:2048
	ds_read_b128 v[158:161], v140 offset:3072
	v_add_u32_e32 v140, s96, v146
	ds_read_b128 v[162:165], v140
	ds_read_b128 v[166:169], v140 offset:1024
	ds_read_b128 v[170:173], v140 offset:2048
	ds_read_b128 v[174:177], v140 offset:3072
	v_lshl_add_u64 v[186:187], s[72:73], 0, v[136:137]
	s_add_i32 m0, s19, 0xc000
	ds_read_b128 v[178:181], v148
	ds_read_b128 v[182:185], v148 offset:1024
	ds_read_b128 v[190:193], v148 offset:2048
	ds_read_b128 v[194:197], v148 offset:3072
	ds_read_b128 v[198:201], v148 offset:4096
	ds_read_b128 v[202:205], v148 offset:5120
	ds_read_b128 v[206:209], v148 offset:6144
	ds_read_b128 v[228:231], v148 offset:7168
	global_load_lds_dwordx4 v[186:187], off
	v_lshl_add_u64 v[186:187], s[72:73], 0, v[138:139]
	s_add_i32 m0, s19, 0xe000
	s_nop 0
	global_load_lds_dwordx4 v[186:187], off
	s_waitcnt vmcnt(8)
	s_waitcnt lgkmcnt(0)
	s_barrier
	v_mfma_f32_16x16x32_bf16 v[124:127], v[142:145], v[178:181], v[124:127]
	v_mfma_f32_16x16x32_bf16 v[120:123], v[154:157], v[178:181], v[120:123]
	v_mfma_f32_16x16x32_bf16 v[116:119], v[142:145], v[190:193], v[116:119]
	v_mfma_f32_16x16x32_bf16 v[112:115], v[154:157], v[190:193], v[112:115]
	v_mfma_f32_16x16x32_bf16 v[108:111], v[142:145], v[198:201], v[108:111]
	v_mfma_f32_16x16x32_bf16 v[104:107], v[154:157], v[198:201], v[104:107]
	v_mfma_f32_16x16x32_bf16 v[100:103], v[142:145], v[206:209], v[100:103]
	v_mfma_f32_16x16x32_bf16 v[96:99], v[154:157], v[206:209], v[96:99]
	v_mfma_f32_16x16x32_bf16 v[124:127], v[150:153], v[182:185], v[124:127]
	v_mfma_f32_16x16x32_bf16 v[120:123], v[158:161], v[182:185], v[120:123]
	v_mfma_f32_16x16x32_bf16 v[116:119], v[150:153], v[194:197], v[116:119]
	v_mfma_f32_16x16x32_bf16 v[112:115], v[158:161], v[194:197], v[112:115]
	v_mfma_f32_16x16x32_bf16 v[108:111], v[150:153], v[202:205], v[108:111]
	v_mfma_f32_16x16x32_bf16 v[104:107], v[158:161], v[202:205], v[104:107]
	v_mfma_f32_16x16x32_bf16 v[100:103], v[150:153], v[228:231], v[100:103]
	v_mfma_f32_16x16x32_bf16 v[96:99], v[158:161], v[228:231], v[96:99]
	v_mfma_f32_16x16x32_bf16 v[92:95], v[162:165], v[178:181], v[92:95]
	v_mfma_f32_16x16x32_bf16 v[88:91], v[170:173], v[178:181], v[88:91]
	v_mfma_f32_16x16x32_bf16 v[84:87], v[162:165], v[190:193], v[84:87]
	v_mfma_f32_16x16x32_bf16 v[80:83], v[170:173], v[190:193], v[80:83]
	v_mfma_f32_16x16x32_bf16 v[76:79], v[162:165], v[198:201], v[76:79]
	v_mfma_f32_16x16x32_bf16 v[72:75], v[170:173], v[198:201], v[72:75]
	v_mfma_f32_16x16x32_bf16 v[68:71], v[162:165], v[206:209], v[68:71]
	v_mfma_f32_16x16x32_bf16 v[64:67], v[170:173], v[206:209], v[64:67]
	v_mfma_f32_16x16x32_bf16 v[92:95], v[166:169], v[182:185], v[92:95]
	v_mfma_f32_16x16x32_bf16 v[88:91], v[174:177], v[182:185], v[88:91]
	v_mfma_f32_16x16x32_bf16 v[84:87], v[166:169], v[194:197], v[84:87]
	v_mfma_f32_16x16x32_bf16 v[80:83], v[174:177], v[194:197], v[80:83]
	v_mfma_f32_16x16x32_bf16 v[76:79], v[166:169], v[202:205], v[76:79]
	v_mfma_f32_16x16x32_bf16 v[72:75], v[174:177], v[202:205], v[72:75]
	v_mfma_f32_16x16x32_bf16 v[68:71], v[166:169], v[228:231], v[68:71]
	v_mfma_f32_16x16x32_bf16 v[64:67], v[174:177], v[228:231], v[64:67]
	s_barrier
	s_add_i32 s84, s84, s18
	v_lshl_add_u64 v[186:187], s[58:59], 0, v[128:129]
	s_mov_b32 m0, s84
	ds_read_b128 v[178:181], v148 offset:16384
	ds_read_b128 v[182:185], v148 offset:17408
	ds_read_b128 v[190:193], v148 offset:18432
	ds_read_b128 v[194:197], v148 offset:19456
	ds_read_b128 v[198:201], v148 offset:20480
	ds_read_b128 v[202:205], v148 offset:21504
	ds_read_b128 v[206:209], v148 offset:22528
	ds_read_b128 v[228:231], v148 offset:23552
	global_load_lds_dwordx4 v[186:187], off
	s_add_i32 m0, s84, 0x2000
	s_add_u32 s84, s58, 0x40000
	v_lshl_add_u64 v[188:189], s[58:59], 0, v[130:131]
	s_addc_u32 s85, s59, 0
	s_add_i32 s96, s96, s18
	global_load_lds_dwordx4 v[188:189], off
	v_lshl_add_u64 v[210:211], s[84:85], 0, v[128:129]
	s_mov_b32 m0, s96
	v_lshl_add_u64 v[232:233], s[64:65], 0, v[132:133]
	global_load_lds_dwordx4 v[210:211], off
	v_lshl_add_u64 v[210:211], s[84:85], 0, v[130:131]
	s_add_i32 m0, s96, 0x2000
	s_nop 0
	global_load_lds_dwordx4 v[210:211], off
	v_lshl_add_u64 v[210:211], s[64:65], 0, v[134:135]
	s_mov_b32 m0, s19
	s_nop 0
	global_load_lds_dwordx4 v[210:211], off
	s_mov_b32 m0, s20
	s_nop 0
	global_load_lds_dwordx4 v[232:233], off
	s_waitcnt vmcnt(8)
	s_waitcnt lgkmcnt(0)
	s_barrier
; #define PG8_STAGE(bufoff, gbase, voff) do { _Pragma("unroll") for (int _i = 0; _i < 2; ++_i) \
;         __builtin_amdgcn_global_load_lds((const unsigned*)((const char*)(gbase) + (voff)[_i]), (PG8_LAS unsigned*)(lds + (bufoff) + ldsw + _i * 8192), 16, 0, 0); } while (0)
; #define PG8_LDA(dst, b, h) do { _Pragma("unroll") for (int m = 0; m < 4; ++m) _Pragma("unroll") for (int k = 0; k < 2; ++k) dst[m][k] = *(const PG8_LAS bf16x8*)(lds + PG8_SA(b, h) + aoff + m * 2048 + k * 1024); } while (0)
; #define PG8_LDB(dst, b, h) do { _Pragma("unroll") for (int n = 0; n < 2; ++n) _Pragma("unroll") for (int k = 0; k < 2; ++k) dst[n][k] = *(const PG8_LAS bf16x8*)(lds + PG8_SB(b, h) + boff + n * 2048 + k * 1024); } while (0)
; #define PG8_MMA(ai, bj, At, Bt) do { __builtin_amdgcn_s_setprio(1); _Pragma("unroll") for (int m = 0; m < 4; ++m) _Pragma("unroll") for (int n = 0; n < 2; ++n) _Pragma("unroll") for (int k = 0; k < 2; ++k) \
;         acc[ai][bj][m][n] = __builtin_amdgcn_mfma_f32_16x16x32_bf16(Bt[n][k], At[m][k], acc[ai][bj][m][n], 0, 0, 0); __builtin_amdgcn_s_setprio(0); } while (0)
; #define PG8_WAIT_V(n) asm volatile("s_waitcnt vmcnt(" #n ")" ::: "memory")
; #define PG8_WAIT_L(n) asm volatile("s_waitcnt lgkmcnt(" #n ")" ::: "memory")
; #define PG8_BAR __builtin_amdgcn_s_barrier()
; #define PG8_SCHED __builtin_amdgcn_sched_barrier(0)
; template <class Epi, class Sched, bool ALIGN_EPI = false, bool SP2 = false>
; __device__ __forceinline__ void gemm_phase(PG8_LAS unsigned char* lds, const Gemm g, const Sched& S, const Epi& E) {
;     ...
;             PG8_WAIT_V(8); PG8_WAIT_L(0); PG8_BAR; PG8_MMA(1, 0, At, B0); PG8_MMA(1, 1, At, B1); PG8_BAR; PG8_SCHED;
;             PG8_LDB(B0, 1, 0); PG8_LDB(B1, 1, 1); PG8_SCHED; PG8_LDA(At, 1, 0); PG8_STAGE(PG8_SA(0, 1), a2 + hstep, voffA);
;             PG8_WAIT_V(8); PG8_WAIT_L(0); PG8_BAR; PG8_MMA(0, 0, At, B0); PG8_MMA(0, 1, At, B1); PG8_BAR; PG8_SCHED;
	v_mfma_f32_16x16x32_bf16 v[60:63], v[142:145], v[178:181], v[60:63]
	v_mfma_f32_16x16x32_bf16 v[56:59], v[154:157], v[178:181], v[56:59]
	v_mfma_f32_16x16x32_bf16 v[52:55], v[142:145], v[190:193], v[52:55]
	v_mfma_f32_16x16x32_bf16 v[48:51], v[154:157], v[190:193], v[48:51]
	v_mfma_f32_16x16x32_bf16 v[44:47], v[142:145], v[198:201], v[44:47]
	v_mfma_f32_16x16x32_bf16 v[40:43], v[154:157], v[198:201], v[40:43]
	v_mfma_f32_16x16x32_bf16 v[36:39], v[142:145], v[206:209], v[36:39]
	v_mfma_f32_16x16x32_bf16 v[32:35], v[154:157], v[206:209], v[32:35]
	v_mfma_f32_16x16x32_bf16 v[60:63], v[150:153], v[182:185], v[60:63]
	v_mfma_f32_16x16x32_bf16 v[56:59], v[158:161], v[182:185], v[56:59]
	v_mfma_f32_16x16x32_bf16 v[52:55], v[150:153], v[194:197], v[52:55]
	v_mfma_f32_16x16x32_bf16 v[48:51], v[158:161], v[194:197], v[48:51]
	v_mfma_f32_16x16x32_bf16 v[44:47], v[150:153], v[202:205], v[44:47]
	v_mfma_f32_16x16x32_bf16 v[40:43], v[158:161], v[202:205], v[40:43]
	v_mfma_f32_16x16x32_bf16 v[36:39], v[150:153], v[228:231], v[36:39]
	v_mfma_f32_16x16x32_bf16 v[32:35], v[158:161], v[228:231], v[32:35]
	v_mfma_f32_16x16x32_bf16 v[28:31], v[162:165], v[178:181], v[28:31]
	v_mfma_f32_16x16x32_bf16 v[24:27], v[170:173], v[178:181], v[24:27]
	v_mfma_f32_16x16x32_bf16 v[20:23], v[162:165], v[190:193], v[20:23]
	v_mfma_f32_16x16x32_bf16 v[16:19], v[170:173], v[190:193], v[16:19]
	v_mfma_f32_16x16x32_bf16 v[12:15], v[162:165], v[198:201], v[12:15]
	v_mfma_f32_16x16x32_bf16 v[8:11], v[170:173], v[198:201], v[8:11]
	v_mfma_f32_16x16x32_bf16 v[4:7], v[162:165], v[206:209], v[4:7]
	v_mfma_f32_16x16x32_bf16 v[0:3], v[170:173], v[206:209], v[0:3]
	v_mfma_f32_16x16x32_bf16 v[28:31], v[166:169], v[182:185], v[28:31]
	v_mfma_f32_16x16x32_bf16 v[24:27], v[174:177], v[182:185], v[24:27]
	v_mfma_f32_16x16x32_bf16 v[20:23], v[166:169], v[194:197], v[20:23]
	v_mfma_f32_16x16x32_bf16 v[16:19], v[174:177], v[194:197], v[16:19]
	v_mfma_f32_16x16x32_bf16 v[12:15], v[166:169], v[202:205], v[12:15]
	v_mfma_f32_16x16x32_bf16 v[8:11], v[174:177], v[202:205], v[8:11]
	v_mfma_f32_16x16x32_bf16 v[4:7], v[166:169], v[228:231], v[4:7]
	v_mfma_f32_16x16x32_bf16 v[0:3], v[174:177], v[228:231], v[0:3]
	s_barrier
	s_add_i32 s84, 0, 0x18000
	v_add_u32_e32 v140, s84, v146
	s_add_i32 s85, 0, 0x1c000
	ds_read_b128 v[142:145], v140
	ds_read_b128 v[150:153], v140 offset:1024
	ds_read_b128 v[154:157], v140 offset:2048
	ds_read_b128 v[158:161], v140 offset:3072
	v_add_u32_e32 v140, s85, v146
	ds_read_b128 v[162:165], v140
	ds_read_b128 v[166:169], v140 offset:1024
	ds_read_b128 v[170:173], v140 offset:2048
	ds_read_b128 v[174:177], v140 offset:3072
	s_add_u32 s64, s64, 0x40000
	s_addc_u32 s65, s65, 0
	s_mov_b32 m0, s21
	v_lshl_add_u64 v[234:235], s[64:65], 0, v[134:135]
	ds_read_b128 v[178:181], v148 offset:32768
	ds_read_b128 v[182:185], v148 offset:33792
	ds_read_b128 v[190:193], v148 offset:34816
	ds_read_b128 v[194:197], v148 offset:35840
	ds_read_b128 v[198:201], v148 offset:36864
	ds_read_b128 v[202:205], v148 offset:37888
	ds_read_b128 v[206:209], v148 offset:38912
	ds_read_b128 v[228:231], v148 offset:39936
	global_load_lds_dwordx4 v[234:235], off
	v_lshl_add_u64 v[234:235], s[64:65], 0, v[132:133]
	s_mov_b32 m0, s22
	s_nop 0
	global_load_lds_dwordx4 v[234:235], off
	s_waitcnt vmcnt(8)
	s_waitcnt lgkmcnt(0)
	s_barrier
	v_mfma_f32_16x16x32_bf16 v[124:127], v[142:145], v[178:181], v[124:127]
	v_mfma_f32_16x16x32_bf16 v[120:123], v[154:157], v[178:181], v[120:123]
	v_mfma_f32_16x16x32_bf16 v[116:119], v[142:145], v[190:193], v[116:119]
	v_mfma_f32_16x16x32_bf16 v[112:115], v[154:157], v[190:193], v[112:115]
	v_mfma_f32_16x16x32_bf16 v[108:111], v[142:145], v[198:201], v[108:111]
	v_mfma_f32_16x16x32_bf16 v[104:107], v[154:157], v[198:201], v[104:107]
	v_mfma_f32_16x16x32_bf16 v[100:103], v[142:145], v[206:209], v[100:103]
	v_mfma_f32_16x16x32_bf16 v[96:99], v[154:157], v[206:209], v[96:99]
	v_mfma_f32_16x16x32_bf16 v[124:127], v[150:153], v[182:185], v[124:127]
	v_mfma_f32_16x16x32_bf16 v[120:123], v[158:161], v[182:185], v[120:123]
	v_mfma_f32_16x16x32_bf16 v[116:119], v[150:153], v[194:197], v[116:119]
	v_mfma_f32_16x16x32_bf16 v[112:115], v[158:161], v[194:197], v[112:115]
	v_mfma_f32_16x16x32_bf16 v[108:111], v[150:153], v[202:205], v[108:111]
	v_mfma_f32_16x16x32_bf16 v[104:107], v[158:161], v[202:205], v[104:107]
	v_mfma_f32_16x16x32_bf16 v[100:103], v[150:153], v[228:231], v[100:103]
	v_mfma_f32_16x16x32_bf16 v[96:99], v[158:161], v[228:231], v[96:99]
	v_mfma_f32_16x16x32_bf16 v[92:95], v[162:165], v[178:181], v[92:95]
	v_mfma_f32_16x16x32_bf16 v[88:91], v[170:173], v[178:181], v[88:91]
	v_mfma_f32_16x16x32_bf16 v[84:87], v[162:165], v[190:193], v[84:87]
	v_mfma_f32_16x16x32_bf16 v[80:83], v[170:173], v[190:193], v[80:83]
	v_mfma_f32_16x16x32_bf16 v[76:79], v[162:165], v[198:201], v[76:79]
	v_mfma_f32_16x16x32_bf16 v[72:75], v[170:173], v[198:201], v[72:75]
	v_mfma_f32_16x16x32_bf16 v[68:71], v[162:165], v[206:209], v[68:71]
	v_mfma_f32_16x16x32_bf16 v[64:67], v[170:173], v[206:209], v[64:67]
	v_mfma_f32_16x16x32_bf16 v[92:95], v[166:169], v[182:185], v[92:95]
	v_mfma_f32_16x16x32_bf16 v[88:91], v[174:177], v[182:185], v[88:91]
	v_mfma_f32_16x16x32_bf16 v[84:87], v[166:169], v[194:197], v[84:87]
	v_mfma_f32_16x16x32_bf16 v[80:83], v[174:177], v[194:197], v[80:83]
	v_mfma_f32_16x16x32_bf16 v[76:79], v[166:169], v[202:205], v[76:79]
	v_mfma_f32_16x16x32_bf16 v[72:75], v[174:177], v[202:205], v[72:75]
	v_mfma_f32_16x16x32_bf16 v[68:71], v[166:169], v[228:231], v[68:71]
	v_mfma_f32_16x16x32_bf16 v[64:67], v[174:177], v[228:231], v[64:67]
	s_barrier
; #define PG8_STAGE(bufoff, gbase, voff) do { _Pragma("unroll") for (int _i = 0; _i < 2; ++_i) \
;         __builtin_amdgcn_global_load_lds((const unsigned*)((const char*)(gbase) + (voff)[_i]), (PG8_LAS unsigned*)(lds + (bufoff) + ldsw + _i * 8192), 16, 0, 0); } while (0)
; #define PG8_LDA(dst, b, h) do { _Pragma("unroll") for (int m = 0; m < 4; ++m) _Pragma("unroll") for (int k = 0; k < 2; ++k) dst[m][k] = *(const PG8_LAS bf16x8*)(lds + PG8_SA(b, h) + aoff + m * 2048 + k * 1024); } while (0)
; #define PG8_MMA(ai, bj, At, Bt) do { __builtin_amdgcn_s_setprio(1); _Pragma("unroll") for (int m = 0; m < 4; ++m) _Pragma("unroll") for (int n = 0; n < 2; ++n) _Pragma("unroll") for (int k = 0; k < 2; ++k) \
;         acc[ai][bj][m][n] = __builtin_amdgcn_mfma_f32_16x16x32_bf16(Bt[n][k], At[m][k], acc[ai][bj][m][n], 0, 0, 0); __builtin_amdgcn_s_setprio(0); } while (0)
; #define PG8_WAIT_V(n) asm volatile("s_waitcnt vmcnt(" #n ")" ::: "memory")
; #define PG8_WAIT_L(n) asm volatile("s_waitcnt lgkmcnt(" #n ")" ::: "memory")
; #define PG8_BAR __builtin_amdgcn_s_barrier()
; #define PG8_SCHED __builtin_amdgcn_sched_barrier(0)
; template <class Epi, class Sched, bool ALIGN_EPI = false, bool SP2 = false>
; __device__ __forceinline__ void gemm_phase(PG8_LAS unsigned char* lds, const Gemm g, const Sched& S, const Epi& E) {
;     ...
;             PG8_LDA(At, 1, 1); PG8_STAGE(PG8_SB(1, 0), b3, voffB); PG8_STAGE(PG8_SB(1, 1), b3 + hstep, voffB); PG8_STAGE(PG8_SA(1, 0), a3, voffA);
;             PG8_WAIT_V(8); PG8_WAIT_L(0); PG8_BAR; PG8_MMA(1, 0, At, B0); PG8_MMA(1, 1, At, B1); PG8_BAR; PG8_SCHED;
	s_add_i32 s64, s84, s18
	v_lshl_add_u64 v[186:187], v[186:187], 0, s[90:91]
	s_mov_b32 m0, s64
	ds_read_b128 v[178:181], v148 offset:49152
	ds_read_b128 v[182:185], v148 offset:50176
	ds_read_b128 v[190:193], v148 offset:51200
	ds_read_b128 v[194:197], v148 offset:52224
	ds_read_b128 v[198:201], v148 offset:53248
	ds_read_b128 v[202:205], v148 offset:54272
	ds_read_b128 v[206:209], v148 offset:55296
	ds_read_b128 v[228:231], v148 offset:56320
	global_load_lds_dwordx4 v[186:187], off
	s_add_i32 m0, s64, 0x2000
	s_add_u32 s58, s58, 0x40080
	v_lshl_add_u64 v[186:187], v[188:189], 0, s[90:91]
	s_addc_u32 s59, s59, 0
	s_add_i32 s64, s85, s18
	global_load_lds_dwordx4 v[186:187], off
	v_lshl_add_u64 v[186:187], s[58:59], 0, v[128:129]
	s_mov_b32 m0, s64
	s_nop 0
	global_load_lds_dwordx4 v[186:187], off
	v_lshl_add_u64 v[186:187], s[58:59], 0, v[130:131]
	s_add_i32 m0, s64, 0x2000
	s_nop 0
	global_load_lds_dwordx4 v[186:187], off
	v_lshl_add_u64 v[186:187], v[210:211], 0, s[90:91]
	s_mov_b32 m0, s28
	s_nop 0
	global_load_lds_dwordx4 v[186:187], off
	v_lshl_add_u64 v[186:187], v[232:233], 0, s[90:91]
	s_mov_b32 m0, s29
	s_nop 0
	global_load_lds_dwordx4 v[186:187], off
	s_waitcnt vmcnt(8)
	s_waitcnt lgkmcnt(0)
	s_barrier
	v_mfma_f32_16x16x32_bf16 v[60:63], v[142:145], v[178:181], v[60:63]
	v_mfma_f32_16x16x32_bf16 v[56:59], v[154:157], v[178:181], v[56:59]
	v_mfma_f32_16x16x32_bf16 v[52:55], v[142:145], v[190:193], v[52:55]
	v_mfma_f32_16x16x32_bf16 v[48:51], v[154:157], v[190:193], v[48:51]
	v_mfma_f32_16x16x32_bf16 v[44:47], v[142:145], v[198:201], v[44:47]
	v_mfma_f32_16x16x32_bf16 v[40:43], v[154:157], v[198:201], v[40:43]
	v_mfma_f32_16x16x32_bf16 v[36:39], v[142:145], v[206:209], v[36:39]
	v_mfma_f32_16x16x32_bf16 v[32:35], v[154:157], v[206:209], v[32:35]
	v_mfma_f32_16x16x32_bf16 v[60:63], v[150:153], v[182:185], v[60:63]
	v_mfma_f32_16x16x32_bf16 v[56:59], v[158:161], v[182:185], v[56:59]
	v_mfma_f32_16x16x32_bf16 v[52:55], v[150:153], v[194:197], v[52:55]
	v_mfma_f32_16x16x32_bf16 v[48:51], v[158:161], v[194:197], v[48:51]
	v_mfma_f32_16x16x32_bf16 v[44:47], v[150:153], v[202:205], v[44:47]
	v_mfma_f32_16x16x32_bf16 v[40:43], v[158:161], v[202:205], v[40:43]
	v_mfma_f32_16x16x32_bf16 v[36:39], v[150:153], v[228:231], v[36:39]
	v_mfma_f32_16x16x32_bf16 v[32:35], v[158:161], v[228:231], v[32:35]
	v_mfma_f32_16x16x32_bf16 v[28:31], v[162:165], v[178:181], v[28:31]
	v_mfma_f32_16x16x32_bf16 v[24:27], v[170:173], v[178:181], v[24:27]
	v_mfma_f32_16x16x32_bf16 v[20:23], v[162:165], v[190:193], v[20:23]
	v_mfma_f32_16x16x32_bf16 v[16:19], v[170:173], v[190:193], v[16:19]
	v_mfma_f32_16x16x32_bf16 v[12:15], v[162:165], v[198:201], v[12:15]
	v_mfma_f32_16x16x32_bf16 v[8:11], v[170:173], v[198:201], v[8:11]
	v_mfma_f32_16x16x32_bf16 v[4:7], v[162:165], v[206:209], v[4:7]
	v_mfma_f32_16x16x32_bf16 v[0:3], v[170:173], v[206:209], v[0:3]
	v_mfma_f32_16x16x32_bf16 v[28:31], v[166:169], v[182:185], v[28:31]
	v_mfma_f32_16x16x32_bf16 v[24:27], v[174:177], v[182:185], v[24:27]
	v_mfma_f32_16x16x32_bf16 v[20:23], v[166:169], v[194:197], v[20:23]
	v_mfma_f32_16x16x32_bf16 v[16:19], v[174:177], v[194:197], v[16:19]
	v_mfma_f32_16x16x32_bf16 v[12:15], v[166:169], v[202:205], v[12:15]
	v_mfma_f32_16x16x32_bf16 v[8:11], v[174:177], v[202:205], v[8:11]
	v_mfma_f32_16x16x32_bf16 v[4:7], v[166:169], v[228:231], v[4:7]
	v_mfma_f32_16x16x32_bf16 v[0:3], v[174:177], v[228:231], v[0:3]
	s_barrier
	s_add_i32 s94, s94, 2
	s_add_u32 s72, s72, 0x100
	s_addc_u32 s73, s73, 0
	s_add_u32 s92, s92, 0x100
	s_addc_u32 s93, s93, 0
	s_cmp_gt_u32 s94, 13
	s_cbranch_scc0 .LBB0_164
	s_and_b64 vcc, exec, s[48:49]
	s_cbranch_vccz .LBB0_167
	s_barrier

; #define PG8_STAGE(bufoff, gbase, voff) do { _Pragma("unroll") for (int _i = 0; _i < 2; ++_i) \
;         __builtin_amdgcn_global_load_lds((const unsigned*)((const char*)(gbase) + (voff)[_i]), (PG8_LAS unsigned*)(lds + (bufoff) + ldsw + _i * 8192), 16, 0, 0); } while (0)
; #define PG8_LDA(dst, b, h) do { _Pragma("unroll") for (int m = 0; m < 4; ++m) _Pragma("unroll") for (int k = 0; k < 2; ++k) dst[m][k] = *(const PG8_LAS bf16x8*)(lds + PG8_SA(b, h) + aoff + m * 2048 + k * 1024); } while (0)
; #define PG8_LDB(dst, b, h) do { _Pragma("unroll") for (int n = 0; n < 2; ++n) _Pragma("unroll") for (int k = 0; k < 2; ++k) dst[n][k] = *(const PG8_LAS bf16x8*)(lds + PG8_SB(b, h) + boff + n * 2048 + k * 1024); } while (0)
; #define PG8_MMA(ai, bj, At, Bt) do { __builtin_amdgcn_s_setprio(1); _Pragma("unroll") for (int m = 0; m < 4; ++m) _Pragma("unroll") for (int n = 0; n < 2; ++n) _Pragma("unroll") for (int k = 0; k < 2; ++k) \
;         acc[ai][bj][m][n] = __builtin_amdgcn_mfma_f32_16x16x32_bf16(Bt[n][k], At[m][k], acc[ai][bj][m][n], 0, 0, 0); __builtin_amdgcn_s_setprio(0); } while (0)
; #define PG8_WAIT_V(n) asm volatile("s_waitcnt vmcnt(" #n ")" ::: "memory")
; #define PG8_BAR __builtin_amdgcn_s_barrier()
; template <class Epi, class Sched, bool ALIGN_EPI = false, bool SP2 = false>
; __device__ __forceinline__ void gemm_phase(PG8_LAS unsigned char* lds, const Gemm g, const Sched& S, const Epi& E) {
;     ...
;         for (int t = 0; t < nt; t += 2) {
;             const bool last = (t == nt - 2);
;             const char* a1 = cA + (size_t)(t + 1) * kstep;
;             const char* a2 = last ? nA : cA + (size_t)(t + 2) * kstep; const char* b2 = last ? nB : cB + (size_t)(t + 2) * kstep;
;             const char* a3 = a2 + kstep; const char* b3 = b2 + kstep;
;             if (last && has_next) S.a_ready(nxt);
;             if constexpr (SP2) {
;             PG8_LDB(B0, 0, 0); PG8_LDB(B1, 0, 1); PG8_SCHED; PG8_LDA(At, 0, 0); PG8_STAGE(PG8_SA(1, 1), a1 + hstep, voffA);
;             PG8_WAIT_V(8); PG8_WAIT_L(0); PG8_BAR; PG8_MMA(0, 0, At, B0); PG8_MMA(0, 1, At, B1); PG8_BAR; PG8_SCHED;
;             PG8_LDA(At, 0, 1); PG8_STAGE(PG8_SB(0, 0), b2, voffB); PG8_STAGE(PG8_SB(0, 1), b2 + hstep, voffB); PG8_STAGE(PG8_SA(0, 0), a2, voffA);
;             PG8_WAIT_V(8); PG8_WAIT_L(0); PG8_BAR; PG8_MMA(1, 0, At, B0); PG8_MMA(1, 1, At, B1); PG8_BAR; PG8_SCHED;
.LBB0_564:
	s_add_u32 s44, vcc_lo, 0xfffc0080
	s_addc_u32 s45, vcc_hi, -1
	s_add_i32 s85, 0, 0x10000
	s_cmp_eq_u32 s84, 12
	s_cselect_b32 s93, s36, s45
	s_cselect_b32 s92, s37, s44
	s_cselect_b32 s59, s67, s94
	s_cselect_b32 s58, s73, s88
	s_add_i32 s8, 0, 0x14000
	v_add_u32_e32 v142, s85, v201
	v_add_u32_e32 v168, s8, v201
	ds_read_b128 v[130:133], v142
	ds_read_b128 v[134:137], v142 offset:1024
	ds_read_b128 v[138:141], v142 offset:2048
	ds_read_b128 v[142:145], v142 offset:3072
	ds_read_b128 v[156:159], v168
	ds_read_b128 v[160:163], v168 offset:1024
	ds_read_b128 v[164:167], v168 offset:2048
	ds_read_b128 v[168:171], v168 offset:3072
	v_lshl_add_u64 v[208:209], vcc, 0, v[152:153]
	s_add_i32 m0, s15, 0xc000
	ds_read_b128 v[172:175], v203
	ds_read_b128 v[176:179], v203 offset:1024
	ds_read_b128 v[180:183], v203 offset:2048
	ds_read_b128 v[184:187], v203 offset:3072
	ds_read_b128 v[188:191], v203 offset:4096
	ds_read_b128 v[192:195], v203 offset:5120
	ds_read_b128 v[196:199], v203 offset:6144
	ds_read_b128 v[204:207], v203 offset:7168
	global_load_lds_dwordx4 v[208:209], off
	v_lshl_add_u64 v[208:209], vcc, 0, v[154:155]
	s_add_i32 m0, s15, 0xe000
	s_nop 0
	global_load_lds_dwordx4 v[208:209], off
	s_waitcnt vmcnt(8)
	s_waitcnt lgkmcnt(0)
	s_barrier
	v_mfma_f32_16x16x32_bf16 v[124:127], v[130:133], v[172:175], v[124:127]
	v_mfma_f32_16x16x32_bf16 v[120:123], v[138:141], v[172:175], v[120:123]
	v_mfma_f32_16x16x32_bf16 v[108:111], v[130:133], v[180:183], v[108:111]
	v_mfma_f32_16x16x32_bf16 v[104:107], v[138:141], v[180:183], v[104:107]
	v_mfma_f32_16x16x32_bf16 v[92:95], v[130:133], v[188:191], v[92:95]
	v_mfma_f32_16x16x32_bf16 v[88:91], v[138:141], v[188:191], v[88:91]
	v_mfma_f32_16x16x32_bf16 v[76:79], v[130:133], v[196:199], v[76:79]
	v_mfma_f32_16x16x32_bf16 v[72:75], v[138:141], v[196:199], v[72:75]
	v_mfma_f32_16x16x32_bf16 v[124:127], v[134:137], v[176:179], v[124:127]
	v_mfma_f32_16x16x32_bf16 v[120:123], v[142:145], v[176:179], v[120:123]
	v_mfma_f32_16x16x32_bf16 v[108:111], v[134:137], v[184:187], v[108:111]
	v_mfma_f32_16x16x32_bf16 v[104:107], v[142:145], v[184:187], v[104:107]
	v_mfma_f32_16x16x32_bf16 v[92:95], v[134:137], v[192:195], v[92:95]
	v_mfma_f32_16x16x32_bf16 v[88:91], v[142:145], v[192:195], v[88:91]
	v_mfma_f32_16x16x32_bf16 v[76:79], v[134:137], v[204:207], v[76:79]
	v_mfma_f32_16x16x32_bf16 v[72:75], v[142:145], v[204:207], v[72:75]
	v_mfma_f32_16x16x32_bf16 v[116:119], v[156:159], v[172:175], v[116:119]
	v_mfma_f32_16x16x32_bf16 v[112:115], v[164:167], v[172:175], v[112:115]
	v_mfma_f32_16x16x32_bf16 v[100:103], v[156:159], v[180:183], v[100:103]
	v_mfma_f32_16x16x32_bf16 v[96:99], v[164:167], v[180:183], v[96:99]
	v_mfma_f32_16x16x32_bf16 v[84:87], v[156:159], v[188:191], v[84:87]
	v_mfma_f32_16x16x32_bf16 v[80:83], v[164:167], v[188:191], v[80:83]
	v_mfma_f32_16x16x32_bf16 v[68:71], v[156:159], v[196:199], v[68:71]
	v_mfma_f32_16x16x32_bf16 v[64:67], v[164:167], v[196:199], v[64:67]
	v_mfma_f32_16x16x32_bf16 v[116:119], v[160:163], v[176:179], v[116:119]
	v_mfma_f32_16x16x32_bf16 v[112:115], v[168:171], v[176:179], v[112:115]
	v_mfma_f32_16x16x32_bf16 v[100:103], v[160:163], v[184:187], v[100:103]
	v_mfma_f32_16x16x32_bf16 v[96:99], v[168:171], v[184:187], v[96:99]
	v_mfma_f32_16x16x32_bf16 v[84:87], v[160:163], v[192:195], v[84:87]
	v_mfma_f32_16x16x32_bf16 v[80:83], v[168:171], v[192:195], v[80:83]
	v_mfma_f32_16x16x32_bf16 v[68:71], v[160:163], v[204:207], v[68:71]
	v_mfma_f32_16x16x32_bf16 v[64:67], v[168:171], v[204:207], v[64:67]
	s_barrier
	s_add_i32 s44, s85, s14
	v_lshl_add_u64 v[208:209], s[58:59], 0, v[128:129]
	s_mov_b32 m0, s44
	ds_read_b128 v[172:175], v203 offset:16384
	ds_read_b128 v[176:179], v203 offset:17408
	ds_read_b128 v[180:183], v203 offset:18432
	ds_read_b128 v[184:187], v203 offset:19456
	ds_read_b128 v[188:191], v203 offset:20480
	ds_read_b128 v[192:195], v203 offset:21504
	ds_read_b128 v[196:199], v203 offset:22528
	ds_read_b128 v[204:207], v203 offset:23552
	global_load_lds_dwordx4 v[208:209], off
	s_add_i32 m0, s44, 0x2000
	s_add_u32 s44, s58, 0x40000
	v_lshl_add_u64 v[210:211], s[58:59], 0, v[146:147]
	s_addc_u32 s45, s59, 0
	s_add_i32 s8, s8, s14
	global_load_lds_dwordx4 v[210:211], off
	v_lshl_add_u64 v[214:215], s[44:45], 0, v[128:129]
	s_mov_b32 m0, s8
	v_lshl_add_u64 v[222:223], s[92:93], 0, v[148:149]
	global_load_lds_dwordx4 v[214:215], off
	v_lshl_add_u64 v[214:215], s[44:45], 0, v[146:147]
	s_add_i32 m0, s8, 0x2000
	s_nop 0
	global_load_lds_dwordx4 v[214:215], off
	v_lshl_add_u64 v[214:215], s[92:93], 0, v[150:151]
	s_mov_b32 m0, s15
	s_nop 0
	global_load_lds_dwordx4 v[214:215], off
	s_mov_b32 m0, s17
	s_nop 0
	global_load_lds_dwordx4 v[222:223], off
	s_waitcnt vmcnt(8)
	s_waitcnt lgkmcnt(0)
	s_barrier
; #define PG8_STAGE(bufoff, gbase, voff) do { _Pragma("unroll") for (int _i = 0; _i < 2; ++_i) \
;         __builtin_amdgcn_global_load_lds((const unsigned*)((const char*)(gbase) + (voff)[_i]), (PG8_LAS unsigned*)(lds + (bufoff) + ldsw + _i * 8192), 16, 0, 0); } while (0)
; #define PG8_LDA(dst, b, h) do { _Pragma("unroll") for (int m = 0; m < 4; ++m) _Pragma("unroll") for (int k = 0; k < 2; ++k) dst[m][k] = *(const PG8_LAS bf16x8*)(lds + PG8_SA(b, h) + aoff + m * 2048 + k * 1024); } while (0)
; #define PG8_LDB(dst, b, h) do { _Pragma("unroll") for (int n = 0; n < 2; ++n) _Pragma("unroll") for (int k = 0; k < 2; ++k) dst[n][k] = *(const PG8_LAS bf16x8*)(lds + PG8_SB(b, h) + boff + n * 2048 + k * 1024); } while (0)
; #define PG8_MMA(ai, bj, At, Bt) do { __builtin_amdgcn_s_setprio(1); _Pragma("unroll") for (int m = 0; m < 4; ++m) _Pragma("unroll") for (int n = 0; n < 2; ++n) _Pragma("unroll") for (int k = 0; k < 2; ++k) \
;         acc[ai][bj][m][n] = __builtin_amdgcn_mfma_f32_16x16x32_bf16(Bt[n][k], At[m][k], acc[ai][bj][m][n], 0, 0, 0); __builtin_amdgcn_s_setprio(0); } while (0)
; #define PG8_WAIT_V(n) asm volatile("s_waitcnt vmcnt(" #n ")" ::: "memory")
; #define PG8_WAIT_L(n) asm volatile("s_waitcnt lgkmcnt(" #n ")" ::: "memory")
; #define PG8_BAR __builtin_amdgcn_s_barrier()
; #define PG8_SCHED __builtin_amdgcn_sched_barrier(0)
; template <class Epi, class Sched, bool ALIGN_EPI = false, bool SP2 = false>
; __device__ __forceinline__ void gemm_phase(PG8_LAS unsigned char* lds, const Gemm g, const Sched& S, const Epi& E) {
;     ...
;             PG8_WAIT_V(8); PG8_WAIT_L(0); PG8_BAR; PG8_MMA(1, 0, At, B0); PG8_MMA(1, 1, At, B1); PG8_BAR; PG8_SCHED;
;             PG8_LDB(B0, 1, 0); PG8_LDB(B1, 1, 1); PG8_SCHED; PG8_LDA(At, 1, 0); PG8_STAGE(PG8_SA(0, 1), a2 + hstep, voffA);
;             PG8_WAIT_V(8); PG8_WAIT_L(0); PG8_BAR; PG8_MMA(0, 0, At, B0); PG8_MMA(0, 1, At, B1); PG8_BAR; PG8_SCHED;
	v_mfma_f32_16x16x32_bf16 v[60:63], v[130:133], v[172:175], v[60:63]
	v_mfma_f32_16x16x32_bf16 v[56:59], v[138:141], v[172:175], v[56:59]
	v_mfma_f32_16x16x32_bf16 v[44:47], v[130:133], v[180:183], v[44:47]
	v_mfma_f32_16x16x32_bf16 v[40:43], v[138:141], v[180:183], v[40:43]
	v_mfma_f32_16x16x32_bf16 v[28:31], v[130:133], v[188:191], v[28:31]
	v_mfma_f32_16x16x32_bf16 v[24:27], v[138:141], v[188:191], v[24:27]
	v_mfma_f32_16x16x32_bf16 v[12:15], v[130:133], v[196:199], v[12:15]
	v_mfma_f32_16x16x32_bf16 v[8:11], v[138:141], v[196:199], v[8:11]
	v_mfma_f32_16x16x32_bf16 v[60:63], v[134:137], v[176:179], v[60:63]
	v_mfma_f32_16x16x32_bf16 v[56:59], v[142:145], v[176:179], v[56:59]
	v_mfma_f32_16x16x32_bf16 v[44:47], v[134:137], v[184:187], v[44:47]
	v_mfma_f32_16x16x32_bf16 v[40:43], v[142:145], v[184:187], v[40:43]
	v_mfma_f32_16x16x32_bf16 v[28:31], v[134:137], v[192:195], v[28:31]
	v_mfma_f32_16x16x32_bf16 v[24:27], v[142:145], v[192:195], v[24:27]
	v_mfma_f32_16x16x32_bf16 v[12:15], v[134:137], v[204:207], v[12:15]
	v_mfma_f32_16x16x32_bf16 v[8:11], v[142:145], v[204:207], v[8:11]
	v_mfma_f32_16x16x32_bf16 v[52:55], v[156:159], v[172:175], v[52:55]
	v_mfma_f32_16x16x32_bf16 v[48:51], v[164:167], v[172:175], v[48:51]
	v_mfma_f32_16x16x32_bf16 v[36:39], v[156:159], v[180:183], v[36:39]
	v_mfma_f32_16x16x32_bf16 v[32:35], v[164:167], v[180:183], v[32:35]
	v_mfma_f32_16x16x32_bf16 v[20:23], v[156:159], v[188:191], v[20:23]
	v_mfma_f32_16x16x32_bf16 v[16:19], v[164:167], v[188:191], v[16:19]
	v_mfma_f32_16x16x32_bf16 v[4:7], v[156:159], v[196:199], v[4:7]
	v_mfma_f32_16x16x32_bf16 v[0:3], v[164:167], v[196:199], v[0:3]
	v_mfma_f32_16x16x32_bf16 v[52:55], v[160:163], v[176:179], v[52:55]
	v_mfma_f32_16x16x32_bf16 v[48:51], v[168:171], v[176:179], v[48:51]
	v_mfma_f32_16x16x32_bf16 v[36:39], v[160:163], v[184:187], v[36:39]
	v_mfma_f32_16x16x32_bf16 v[32:35], v[168:171], v[184:187], v[32:35]
	v_mfma_f32_16x16x32_bf16 v[20:23], v[160:163], v[192:195], v[20:23]
	v_mfma_f32_16x16x32_bf16 v[16:19], v[168:171], v[192:195], v[16:19]
	v_mfma_f32_16x16x32_bf16 v[4:7], v[160:163], v[204:207], v[4:7]
	v_mfma_f32_16x16x32_bf16 v[0:3], v[168:171], v[204:207], v[0:3]
	s_barrier
	s_add_i32 s8, 0, 0x18000
	s_add_i32 s85, 0, 0x1c000
	v_add_u32_e32 v142, s8, v201
	v_add_u32_e32 v168, s85, v201
	ds_read_b128 v[130:133], v142
	ds_read_b128 v[134:137], v142 offset:1024
	ds_read_b128 v[138:141], v142 offset:2048
	ds_read_b128 v[142:145], v142 offset:3072
	ds_read_b128 v[156:159], v168
	ds_read_b128 v[160:163], v168 offset:1024
	ds_read_b128 v[164:167], v168 offset:2048
	ds_read_b128 v[168:171], v168 offset:3072
	s_add_u32 s44, s92, 0x40000
	s_addc_u32 s45, s93, 0
	s_mov_b32 m0, s18
	v_lshl_add_u64 v[228:229], s[44:45], 0, v[150:151]
	ds_read_b128 v[172:175], v203 offset:32768
	ds_read_b128 v[176:179], v203 offset:33792
	ds_read_b128 v[180:183], v203 offset:34816
	ds_read_b128 v[184:187], v203 offset:35840
	ds_read_b128 v[188:191], v203 offset:36864
	ds_read_b128 v[192:195], v203 offset:37888
	ds_read_b128 v[196:199], v203 offset:38912
	ds_read_b128 v[204:207], v203 offset:39936
	global_load_lds_dwordx4 v[228:229], off
	v_lshl_add_u64 v[228:229], s[44:45], 0, v[148:149]
	s_mov_b32 m0, s19
	s_nop 0
	global_load_lds_dwordx4 v[228:229], off
	s_waitcnt vmcnt(8)
	s_waitcnt lgkmcnt(0)
	s_barrier
	v_mfma_f32_16x16x32_bf16 v[124:127], v[130:133], v[172:175], v[124:127]
	v_mfma_f32_16x16x32_bf16 v[120:123], v[138:141], v[172:175], v[120:123]
	v_mfma_f32_16x16x32_bf16 v[108:111], v[130:133], v[180:183], v[108:111]
	v_mfma_f32_16x16x32_bf16 v[104:107], v[138:141], v[180:183], v[104:107]
	v_mfma_f32_16x16x32_bf16 v[92:95], v[130:133], v[188:191], v[92:95]
	v_mfma_f32_16x16x32_bf16 v[88:91], v[138:141], v[188:191], v[88:91]
	v_mfma_f32_16x16x32_bf16 v[76:79], v[130:133], v[196:199], v[76:79]
	v_mfma_f32_16x16x32_bf16 v[72:75], v[138:141], v[196:199], v[72:75]
	v_mfma_f32_16x16x32_bf16 v[124:127], v[134:137], v[176:179], v[124:127]
	v_mfma_f32_16x16x32_bf16 v[120:123], v[142:145], v[176:179], v[120:123]
	v_mfma_f32_16x16x32_bf16 v[108:111], v[134:137], v[184:187], v[108:111]
	v_mfma_f32_16x16x32_bf16 v[104:107], v[142:145], v[184:187], v[104:107]
	v_mfma_f32_16x16x32_bf16 v[92:95], v[134:137], v[192:195], v[92:95]
	v_mfma_f32_16x16x32_bf16 v[88:91], v[142:145], v[192:195], v[88:91]
	v_mfma_f32_16x16x32_bf16 v[76:79], v[134:137], v[204:207], v[76:79]
	v_mfma_f32_16x16x32_bf16 v[72:75], v[142:145], v[204:207], v[72:75]
	v_mfma_f32_16x16x32_bf16 v[116:119], v[156:159], v[172:175], v[116:119]
	v_mfma_f32_16x16x32_bf16 v[112:115], v[164:167], v[172:175], v[112:115]
	v_mfma_f32_16x16x32_bf16 v[100:103], v[156:159], v[180:183], v[100:103]
	v_mfma_f32_16x16x32_bf16 v[96:99], v[164:167], v[180:183], v[96:99]
	v_mfma_f32_16x16x32_bf16 v[84:87], v[156:159], v[188:191], v[84:87]
	v_mfma_f32_16x16x32_bf16 v[80:83], v[164:167], v[188:191], v[80:83]
	v_mfma_f32_16x16x32_bf16 v[68:71], v[156:159], v[196:199], v[68:71]
	v_mfma_f32_16x16x32_bf16 v[64:67], v[164:167], v[196:199], v[64:67]
	v_mfma_f32_16x16x32_bf16 v[116:119], v[160:163], v[176:179], v[116:119]
	v_mfma_f32_16x16x32_bf16 v[112:115], v[168:171], v[176:179], v[112:115]
	v_mfma_f32_16x16x32_bf16 v[100:103], v[160:163], v[184:187], v[100:103]
	v_mfma_f32_16x16x32_bf16 v[96:99], v[168:171], v[184:187], v[96:99]
	v_mfma_f32_16x16x32_bf16 v[84:87], v[160:163], v[192:195], v[84:87]
	v_mfma_f32_16x16x32_bf16 v[80:83], v[168:171], v[192:195], v[80:83]
	v_mfma_f32_16x16x32_bf16 v[68:71], v[160:163], v[204:207], v[68:71]
	v_mfma_f32_16x16x32_bf16 v[64:67], v[168:171], v[204:207], v[64:67]
	s_barrier
; #define PG8_STAGE(bufoff, gbase, voff) do { _Pragma("unroll") for (int _i = 0; _i < 2; ++_i) \
;         __builtin_amdgcn_global_load_lds((const unsigned*)((const char*)(gbase) + (voff)[_i]), (PG8_LAS unsigned*)(lds + (bufoff) + ldsw + _i * 8192), 16, 0, 0); } while (0)
; #define PG8_LDA(dst, b, h) do { _Pragma("unroll") for (int m = 0; m < 4; ++m) _Pragma("unroll") for (int k = 0; k < 2; ++k) dst[m][k] = *(const PG8_LAS bf16x8*)(lds + PG8_SA(b, h) + aoff + m * 2048 + k * 1024); } while (0)
; #define PG8_MMA(ai, bj, At, Bt) do { __builtin_amdgcn_s_setprio(1); _Pragma("unroll") for (int m = 0; m < 4; ++m) _Pragma("unroll") for (int n = 0; n < 2; ++n) _Pragma("unroll") for (int k = 0; k < 2; ++k) \
;         acc[ai][bj][m][n] = __builtin_amdgcn_mfma_f32_16x16x32_bf16(Bt[n][k], At[m][k], acc[ai][bj][m][n], 0, 0, 0); __builtin_amdgcn_s_setprio(0); } while (0)
; #define PG8_WAIT_V(n) asm volatile("s_waitcnt vmcnt(" #n ")" ::: "memory")
; #define PG8_WAIT_L(n) asm volatile("s_waitcnt lgkmcnt(" #n ")" ::: "memory")
; #define PG8_BAR __builtin_amdgcn_s_barrier()
; #define PG8_SCHED __builtin_amdgcn_sched_barrier(0)
; template <class Epi, class Sched, bool ALIGN_EPI = false, bool SP2 = false>
; __device__ __forceinline__ void gemm_phase(PG8_LAS unsigned char* lds, const Gemm g, const Sched& S, const Epi& E) {
;     ...
;             PG8_LDA(At, 1, 1); PG8_STAGE(PG8_SB(1, 0), b3, voffB); PG8_STAGE(PG8_SB(1, 1), b3 + hstep, voffB); PG8_STAGE(PG8_SA(1, 0), a3, voffA);
;             PG8_WAIT_V(8); PG8_WAIT_L(0); PG8_BAR; PG8_MMA(1, 0, At, B0); PG8_MMA(1, 1, At, B1); PG8_BAR; PG8_SCHED;
	s_add_i32 s8, s8, s14
	v_lshl_add_u64 v[208:209], v[208:209], 0, s[90:91]
	s_mov_b32 m0, s8
	ds_read_b128 v[172:175], v203 offset:49152
	ds_read_b128 v[176:179], v203 offset:50176
	ds_read_b128 v[180:183], v203 offset:51200
	ds_read_b128 v[184:187], v203 offset:52224
	ds_read_b128 v[188:191], v203 offset:53248
	ds_read_b128 v[192:195], v203 offset:54272
	ds_read_b128 v[196:199], v203 offset:55296
	ds_read_b128 v[204:207], v203 offset:56320
	global_load_lds_dwordx4 v[208:209], off
	s_add_i32 m0, s8, 0x2000
	s_add_u32 s44, s58, 0x40080
	v_lshl_add_u64 v[208:209], v[210:211], 0, s[90:91]
	s_addc_u32 s45, s59, 0
	s_add_i32 s8, s85, s14
	global_load_lds_dwordx4 v[208:209], off
	v_lshl_add_u64 v[208:209], s[44:45], 0, v[128:129]
	s_mov_b32 m0, s8
	s_nop 0
	global_load_lds_dwordx4 v[208:209], off
	v_lshl_add_u64 v[208:209], s[44:45], 0, v[146:147]
	s_add_i32 m0, s8, 0x2000
	s_nop 0
	global_load_lds_dwordx4 v[208:209], off
	v_lshl_add_u64 v[208:209], v[214:215], 0, s[90:91]
	s_mov_b32 m0, s30
	s_nop 0
	global_load_lds_dwordx4 v[208:209], off
	v_lshl_add_u64 v[208:209], v[222:223], 0, s[90:91]
	s_mov_b32 m0, s31
	s_nop 0
	global_load_lds_dwordx4 v[208:209], off
	s_waitcnt vmcnt(8)
	s_waitcnt lgkmcnt(0)
	s_barrier
	v_mfma_f32_16x16x32_bf16 v[60:63], v[130:133], v[172:175], v[60:63]
	v_mfma_f32_16x16x32_bf16 v[56:59], v[138:141], v[172:175], v[56:59]
	v_mfma_f32_16x16x32_bf16 v[44:47], v[130:133], v[180:183], v[44:47]
	v_mfma_f32_16x16x32_bf16 v[40:43], v[138:141], v[180:183], v[40:43]
	v_mfma_f32_16x16x32_bf16 v[28:31], v[130:133], v[188:191], v[28:31]
	v_mfma_f32_16x16x32_bf16 v[24:27], v[138:141], v[188:191], v[24:27]
	v_mfma_f32_16x16x32_bf16 v[12:15], v[130:133], v[196:199], v[12:15]
	v_mfma_f32_16x16x32_bf16 v[8:11], v[138:141], v[196:199], v[8:11]
	v_mfma_f32_16x16x32_bf16 v[60:63], v[134:137], v[176:179], v[60:63]
	v_mfma_f32_16x16x32_bf16 v[56:59], v[142:145], v[176:179], v[56:59]
	v_mfma_f32_16x16x32_bf16 v[44:47], v[134:137], v[184:187], v[44:47]
	v_mfma_f32_16x16x32_bf16 v[40:43], v[142:145], v[184:187], v[40:43]
	v_mfma_f32_16x16x32_bf16 v[28:31], v[134:137], v[192:195], v[28:31]
	v_mfma_f32_16x16x32_bf16 v[24:27], v[142:145], v[192:195], v[24:27]
	v_mfma_f32_16x16x32_bf16 v[12:15], v[134:137], v[204:207], v[12:15]
	v_mfma_f32_16x16x32_bf16 v[8:11], v[142:145], v[204:207], v[8:11]
	v_mfma_f32_16x16x32_bf16 v[52:55], v[156:159], v[172:175], v[52:55]
	v_mfma_f32_16x16x32_bf16 v[48:51], v[164:167], v[172:175], v[48:51]
	v_mfma_f32_16x16x32_bf16 v[36:39], v[156:159], v[180:183], v[36:39]
	v_mfma_f32_16x16x32_bf16 v[32:35], v[164:167], v[180:183], v[32:35]
	v_mfma_f32_16x16x32_bf16 v[20:23], v[156:159], v[188:191], v[20:23]
	v_mfma_f32_16x16x32_bf16 v[16:19], v[164:167], v[188:191], v[16:19]
	v_mfma_f32_16x16x32_bf16 v[4:7], v[156:159], v[196:199], v[4:7]
	v_mfma_f32_16x16x32_bf16 v[0:3], v[164:167], v[196:199], v[0:3]
	v_mfma_f32_16x16x32_bf16 v[52:55], v[160:163], v[176:179], v[52:55]
	v_mfma_f32_16x16x32_bf16 v[48:51], v[168:171], v[176:179], v[48:51]
	v_mfma_f32_16x16x32_bf16 v[36:39], v[160:163], v[184:187], v[36:39]
	v_mfma_f32_16x16x32_bf16 v[32:35], v[168:171], v[184:187], v[32:35]
	v_mfma_f32_16x16x32_bf16 v[20:23], v[160:163], v[192:195], v[20:23]
	v_mfma_f32_16x16x32_bf16 v[16:19], v[168:171], v[192:195], v[16:19]
	v_mfma_f32_16x16x32_bf16 v[4:7], v[160:163], v[204:207], v[4:7]
	v_mfma_f32_16x16x32_bf16 v[0:3], v[168:171], v[204:207], v[0:3]
	s_barrier
	s_add_i32 s84, s84, 2
	s_add_u32 vcc_lo, vcc_lo, 0x100
	s_addc_u32 vcc_hi, vcc_hi, 0
	s_add_u32 s88, s88, 0x100
	s_addc_u32 s94, s94, 0
	s_cmp_gt_u32 s84, 13
	s_cbranch_scc0 .LBB0_564
	s_and_b64 vcc, exec, s[62:63]
	s_cbranch_vccz .LBB0_567
	s_barrier

; #define PG8_STAGE(bufoff, gbase, voff) do { _Pragma("unroll") for (int _i = 0; _i < 2; ++_i) \
;         __builtin_amdgcn_global_load_lds((const unsigned*)((const char*)(gbase) + (voff)[_i]), (PG8_LAS unsigned*)(lds + (bufoff) + ldsw + _i * 8192), 16, 0, 0); } while (0)
; #define PG8_LDA(dst, b, h) do { _Pragma("unroll") for (int m = 0; m < 4; ++m) _Pragma("unroll") for (int k = 0; k < 2; ++k) dst[m][k] = *(const PG8_LAS bf16x8*)(lds + PG8_SA(b, h) + aoff + m * 2048 + k * 1024); } while (0)
; #define PG8_LDB(dst, b, h) do { _Pragma("unroll") for (int n = 0; n < 2; ++n) _Pragma("unroll") for (int k = 0; k < 2; ++k) dst[n][k] = *(const PG8_LAS bf16x8*)(lds + PG8_SB(b, h) + boff + n * 2048 + k * 1024); } while (0)
; #define PG8_MMA(ai, bj, At, Bt) do { __builtin_amdgcn_s_setprio(1); _Pragma("unroll") for (int m = 0; m < 4; ++m) _Pragma("unroll") for (int n = 0; n < 2; ++n) _Pragma("unroll") for (int k = 0; k < 2; ++k) \
;         acc[ai][bj][m][n] = __builtin_amdgcn_mfma_f32_16x16x32_bf16(Bt[n][k], At[m][k], acc[ai][bj][m][n], 0, 0, 0); __builtin_amdgcn_s_setprio(0); } while (0)
; #define PG8_WAIT_V(n) asm volatile("s_waitcnt vmcnt(" #n ")" ::: "memory")
; #define PG8_BAR __builtin_amdgcn_s_barrier()
; template <class Epi, class Sched, bool ALIGN_EPI = false, bool SP2 = false>
; __device__ __forceinline__ void gemm_phase(PG8_LAS unsigned char* lds, const Gemm g, const Sched& S, const Epi& E) {
;     ...
;         for (int t = 0; t < nt; t += 2) {
;             const bool last = (t == nt - 2);
;             const char* a1 = cA + (size_t)(t + 1) * kstep;
;             const char* a2 = last ? nA : cA + (size_t)(t + 2) * kstep; const char* b2 = last ? nB : cB + (size_t)(t + 2) * kstep;
;             const char* a3 = a2 + kstep; const char* b3 = b2 + kstep;
;             if (last && has_next) S.a_ready(nxt);
;             if constexpr (SP2) {
;             PG8_LDB(B0, 0, 0); PG8_LDB(B1, 0, 1); PG8_SCHED; PG8_LDA(At, 0, 0); PG8_STAGE(PG8_SA(1, 1), a1 + hstep, voffA);
;             PG8_WAIT_V(8); PG8_WAIT_L(0); PG8_BAR; PG8_MMA(0, 0, At, B0); PG8_MMA(0, 1, At, B1); PG8_BAR; PG8_SCHED;
;             PG8_LDA(At, 0, 1); PG8_STAGE(PG8_SB(0, 0), b2, voffB); PG8_STAGE(PG8_SB(0, 1), b2 + hstep, voffB); PG8_STAGE(PG8_SA(0, 0), a2, voffA);
;             PG8_WAIT_V(8); PG8_WAIT_L(0); PG8_BAR; PG8_MMA(1, 0, At, B0); PG8_MMA(1, 1, At, B1); PG8_BAR; PG8_SCHED;
.LBB0_598:
	s_add_u32 s58, vcc_lo, 0xfffc0080
	s_addc_u32 s59, vcc_hi, -1
	s_add_i32 s84, 0, 0x10000
	s_cmp_eq_u32 s94, 12
	s_cselect_b32 s65, s35, s59
	s_cselect_b32 s64, s36, s58
	s_cselect_b32 s59, s37, s93
	s_cselect_b32 s58, s43, s88
	s_add_i32 s97, 0, 0x14000
	v_add_u32_e32 v76, s84, v228
	v_add_u32_e32 v168, s97, v228
	ds_read_b128 v[64:67], v76
	ds_read_b128 v[68:71], v76 offset:1024
	ds_read_b128 v[72:75], v76 offset:2048
	ds_read_b128 v[76:79], v76 offset:3072
	ds_read_b128 v[156:159], v168
	ds_read_b128 v[160:163], v168 offset:1024
	ds_read_b128 v[164:167], v168 offset:2048
	ds_read_b128 v[168:171], v168 offset:3072
	v_lshl_add_u64 v[204:205], vcc, 0, v[152:153]
	s_add_i32 m0, s18, 0xc000
	ds_read_b128 v[172:175], v230
	ds_read_b128 v[176:179], v230 offset:1024
	ds_read_b128 v[180:183], v230 offset:2048
	ds_read_b128 v[184:187], v230 offset:3072
	ds_read_b128 v[188:191], v230 offset:4096
	ds_read_b128 v[192:195], v230 offset:5120
	ds_read_b128 v[196:199], v230 offset:6144
	ds_read_b128 v[200:203], v230 offset:7168
	global_load_lds_dwordx4 v[204:205], off
	v_lshl_add_u64 v[204:205], vcc, 0, v[154:155]
	s_add_i32 m0, s18, 0xe000
	s_nop 0
	global_load_lds_dwordx4 v[204:205], off
	s_waitcnt vmcnt(8)
	s_waitcnt lgkmcnt(0)
	s_barrier
	v_mfma_f32_16x16x32_bf16 v[142:145], v[64:67], v[172:175], v[142:145]
	v_mfma_f32_16x16x32_bf16 v[138:141], v[72:75], v[172:175], v[138:141]
	v_mfma_f32_16x16x32_bf16 v[134:137], v[64:67], v[180:183], v[134:137]
	v_mfma_f32_16x16x32_bf16 v[124:127], v[72:75], v[180:183], v[124:127]
	v_mfma_f32_16x16x32_bf16 v[108:111], v[64:67], v[188:191], v[108:111]
	v_mfma_f32_16x16x32_bf16 v[104:107], v[72:75], v[188:191], v[104:107]
	v_mfma_f32_16x16x32_bf16 v[100:103], v[64:67], v[196:199], v[100:103]
	v_mfma_f32_16x16x32_bf16 v[92:95], v[72:75], v[196:199], v[92:95]
	v_mfma_f32_16x16x32_bf16 v[142:145], v[68:71], v[176:179], v[142:145]
	v_mfma_f32_16x16x32_bf16 v[138:141], v[76:79], v[176:179], v[138:141]
	v_mfma_f32_16x16x32_bf16 v[134:137], v[68:71], v[184:187], v[134:137]
	v_mfma_f32_16x16x32_bf16 v[124:127], v[76:79], v[184:187], v[124:127]
	v_mfma_f32_16x16x32_bf16 v[108:111], v[68:71], v[192:195], v[108:111]
	v_mfma_f32_16x16x32_bf16 v[104:107], v[76:79], v[192:195], v[104:107]
	v_mfma_f32_16x16x32_bf16 v[100:103], v[68:71], v[200:203], v[100:103]
	v_mfma_f32_16x16x32_bf16 v[92:95], v[76:79], v[200:203], v[92:95]
	v_mfma_f32_16x16x32_bf16 v[130:133], v[156:159], v[172:175], v[130:133]
	v_mfma_f32_16x16x32_bf16 v[120:123], v[164:167], v[172:175], v[120:123]
	v_mfma_f32_16x16x32_bf16 v[116:119], v[156:159], v[180:183], v[116:119]
	v_mfma_f32_16x16x32_bf16 v[112:115], v[164:167], v[180:183], v[112:115]
	v_mfma_f32_16x16x32_bf16 v[96:99], v[156:159], v[188:191], v[96:99]
	v_mfma_f32_16x16x32_bf16 v[88:91], v[164:167], v[188:191], v[88:91]
	v_mfma_f32_16x16x32_bf16 v[84:87], v[156:159], v[196:199], v[84:87]
	v_mfma_f32_16x16x32_bf16 v[80:83], v[164:167], v[196:199], v[80:83]
	v_mfma_f32_16x16x32_bf16 v[130:133], v[160:163], v[176:179], v[130:133]
	v_mfma_f32_16x16x32_bf16 v[120:123], v[168:171], v[176:179], v[120:123]
	v_mfma_f32_16x16x32_bf16 v[116:119], v[160:163], v[184:187], v[116:119]
	v_mfma_f32_16x16x32_bf16 v[112:115], v[168:171], v[184:187], v[112:115]
	v_mfma_f32_16x16x32_bf16 v[96:99], v[160:163], v[192:195], v[96:99]
	v_mfma_f32_16x16x32_bf16 v[88:91], v[168:171], v[192:195], v[88:91]
	v_mfma_f32_16x16x32_bf16 v[84:87], v[160:163], v[200:203], v[84:87]
	v_mfma_f32_16x16x32_bf16 v[80:83], v[168:171], v[200:203], v[80:83]
	s_barrier
	s_add_i32 s84, s84, s17
	v_lshl_add_u64 v[204:205], s[58:59], 0, v[128:129]
	s_mov_b32 m0, s84
	ds_read_b128 v[172:175], v230 offset:16384
	ds_read_b128 v[176:179], v230 offset:17408
	ds_read_b128 v[180:183], v230 offset:18432
	ds_read_b128 v[184:187], v230 offset:19456
	ds_read_b128 v[188:191], v230 offset:20480
	ds_read_b128 v[192:195], v230 offset:21504
	ds_read_b128 v[196:199], v230 offset:22528
	ds_read_b128 v[200:203], v230 offset:23552
	global_load_lds_dwordx4 v[204:205], off
	s_add_i32 m0, s84, 0x2000
	s_add_u32 s84, s58, 0x40000
	v_lshl_add_u64 v[206:207], s[58:59], 0, v[146:147]
	s_addc_u32 s85, s59, 0
	s_add_i32 s97, s97, s17
	global_load_lds_dwordx4 v[206:207], off
	v_lshl_add_u64 v[208:209], s[84:85], 0, v[128:129]
	s_mov_b32 m0, s97
	v_lshl_add_u64 v[210:211], s[64:65], 0, v[148:149]
	global_load_lds_dwordx4 v[208:209], off
	v_lshl_add_u64 v[208:209], s[84:85], 0, v[146:147]
	s_add_i32 m0, s97, 0x2000
	s_nop 0
	global_load_lds_dwordx4 v[208:209], off
	v_lshl_add_u64 v[208:209], s[64:65], 0, v[150:151]
	s_mov_b32 m0, s18
	s_nop 0
	global_load_lds_dwordx4 v[208:209], off
	s_mov_b32 m0, s19
	s_nop 0
	global_load_lds_dwordx4 v[210:211], off
	s_waitcnt vmcnt(8)
	s_waitcnt lgkmcnt(0)
	s_barrier
; #define PG8_STAGE(bufoff, gbase, voff) do { _Pragma("unroll") for (int _i = 0; _i < 2; ++_i) \
;         __builtin_amdgcn_global_load_lds((const unsigned*)((const char*)(gbase) + (voff)[_i]), (PG8_LAS unsigned*)(lds + (bufoff) + ldsw + _i * 8192), 16, 0, 0); } while (0)
; #define PG8_LDA(dst, b, h) do { _Pragma("unroll") for (int m = 0; m < 4; ++m) _Pragma("unroll") for (int k = 0; k < 2; ++k) dst[m][k] = *(const PG8_LAS bf16x8*)(lds + PG8_SA(b, h) + aoff + m * 2048 + k * 1024); } while (0)
; #define PG8_LDB(dst, b, h) do { _Pragma("unroll") for (int n = 0; n < 2; ++n) _Pragma("unroll") for (int k = 0; k < 2; ++k) dst[n][k] = *(const PG8_LAS bf16x8*)(lds + PG8_SB(b, h) + boff + n * 2048 + k * 1024); } while (0)
; #define PG8_MMA(ai, bj, At, Bt) do { __builtin_amdgcn_s_setprio(1); _Pragma("unroll") for (int m = 0; m < 4; ++m) _Pragma("unroll") for (int n = 0; n < 2; ++n) _Pragma("unroll") for (int k = 0; k < 2; ++k) \
;         acc[ai][bj][m][n] = __builtin_amdgcn_mfma_f32_16x16x32_bf16(Bt[n][k], At[m][k], acc[ai][bj][m][n], 0, 0, 0); __builtin_amdgcn_s_setprio(0); } while (0)
; #define PG8_WAIT_V(n) asm volatile("s_waitcnt vmcnt(" #n ")" ::: "memory")
; #define PG8_WAIT_L(n) asm volatile("s_waitcnt lgkmcnt(" #n ")" ::: "memory")
; #define PG8_BAR __builtin_amdgcn_s_barrier()
; #define PG8_SCHED __builtin_amdgcn_sched_barrier(0)
; template <class Epi, class Sched, bool ALIGN_EPI = false, bool SP2 = false>
; __device__ __forceinline__ void gemm_phase(PG8_LAS unsigned char* lds, const Gemm g, const Sched& S, const Epi& E) {
;     ...
;             PG8_WAIT_V(8); PG8_WAIT_L(0); PG8_BAR; PG8_MMA(0, 0, At, B0); PG8_MMA(0, 1, At, B1); PG8_BAR; PG8_SCHED;
;             PG8_LDA(At, 0, 1); PG8_STAGE(PG8_SB(0, 0), b2, voffB); PG8_STAGE(PG8_SB(0, 1), b2 + hstep, voffB); PG8_STAGE(PG8_SA(0, 0), a2, voffA);
;             PG8_WAIT_V(8); PG8_WAIT_L(0); PG8_BAR; PG8_MMA(1, 0, At, B0); PG8_MMA(1, 1, At, B1); PG8_BAR; PG8_SCHED;
;             PG8_LDB(B0, 1, 0); PG8_LDB(B1, 1, 1); PG8_SCHED; PG8_LDA(At, 1, 0); PG8_STAGE(PG8_SA(0, 1), a2 + hstep, voffA);
;             PG8_WAIT_V(8); PG8_WAIT_L(0); PG8_BAR; PG8_MMA(0, 0, At, B0); PG8_MMA(0, 1, At, B1); PG8_BAR; PG8_SCHED;
	v_mfma_f32_16x16x32_bf16 v[60:63], v[64:67], v[172:175], v[60:63]
	v_mfma_f32_16x16x32_bf16 v[56:59], v[72:75], v[172:175], v[56:59]
	v_mfma_f32_16x16x32_bf16 v[52:55], v[64:67], v[180:183], v[52:55]
	v_mfma_f32_16x16x32_bf16 v[44:47], v[72:75], v[180:183], v[44:47]
	v_mfma_f32_16x16x32_bf16 v[28:31], v[64:67], v[188:191], v[28:31]
	v_mfma_f32_16x16x32_bf16 v[24:27], v[72:75], v[188:191], v[24:27]
	v_mfma_f32_16x16x32_bf16 v[12:15], v[64:67], v[196:199], v[12:15]
	v_mfma_f32_16x16x32_bf16 v[8:11], v[72:75], v[196:199], v[8:11]
	v_mfma_f32_16x16x32_bf16 v[60:63], v[68:71], v[176:179], v[60:63]
	v_mfma_f32_16x16x32_bf16 v[56:59], v[76:79], v[176:179], v[56:59]
	v_mfma_f32_16x16x32_bf16 v[52:55], v[68:71], v[184:187], v[52:55]
	v_mfma_f32_16x16x32_bf16 v[44:47], v[76:79], v[184:187], v[44:47]
	v_mfma_f32_16x16x32_bf16 v[28:31], v[68:71], v[192:195], v[28:31]
	v_mfma_f32_16x16x32_bf16 v[24:27], v[76:79], v[192:195], v[24:27]
	v_mfma_f32_16x16x32_bf16 v[12:15], v[68:71], v[200:203], v[12:15]
	v_mfma_f32_16x16x32_bf16 v[8:11], v[76:79], v[200:203], v[8:11]
	v_mfma_f32_16x16x32_bf16 v[48:51], v[156:159], v[172:175], v[48:51]
	v_mfma_f32_16x16x32_bf16 v[40:43], v[164:167], v[172:175], v[40:43]
	v_mfma_f32_16x16x32_bf16 v[36:39], v[156:159], v[180:183], v[36:39]
	v_mfma_f32_16x16x32_bf16 v[32:35], v[164:167], v[180:183], v[32:35]
	v_mfma_f32_16x16x32_bf16 v[20:23], v[156:159], v[188:191], v[20:23]
	v_mfma_f32_16x16x32_bf16 v[16:19], v[164:167], v[188:191], v[16:19]
	v_mfma_f32_16x16x32_bf16 v[4:7], v[156:159], v[196:199], v[4:7]
	v_mfma_f32_16x16x32_bf16 v[0:3], v[164:167], v[196:199], v[0:3]
	v_mfma_f32_16x16x32_bf16 v[48:51], v[160:163], v[176:179], v[48:51]
	v_mfma_f32_16x16x32_bf16 v[40:43], v[168:171], v[176:179], v[40:43]
	v_mfma_f32_16x16x32_bf16 v[36:39], v[160:163], v[184:187], v[36:39]
	v_mfma_f32_16x16x32_bf16 v[32:35], v[168:171], v[184:187], v[32:35]
	v_mfma_f32_16x16x32_bf16 v[20:23], v[160:163], v[192:195], v[20:23]
	v_mfma_f32_16x16x32_bf16 v[16:19], v[168:171], v[192:195], v[16:19]
	v_mfma_f32_16x16x32_bf16 v[4:7], v[160:163], v[200:203], v[4:7]
	v_mfma_f32_16x16x32_bf16 v[0:3], v[168:171], v[200:203], v[0:3]
	s_barrier
	s_add_i32 s84, 0, 0x18000
	s_add_i32 s85, 0, 0x1c000
	v_add_u32_e32 v76, s84, v228
	v_add_u32_e32 v168, s85, v228
	ds_read_b128 v[64:67], v76
	ds_read_b128 v[68:71], v76 offset:1024
	ds_read_b128 v[72:75], v76 offset:2048
	ds_read_b128 v[76:79], v76 offset:3072
	ds_read_b128 v[156:159], v168
	ds_read_b128 v[160:163], v168 offset:1024
	ds_read_b128 v[164:167], v168 offset:2048
	ds_read_b128 v[168:171], v168 offset:3072
	s_add_u32 s64, s64, 0x40000
	s_addc_u32 s65, s65, 0
	s_mov_b32 m0, s20
	v_lshl_add_u64 v[214:215], s[64:65], 0, v[150:151]
	ds_read_b128 v[172:175], v230 offset:32768
	ds_read_b128 v[176:179], v230 offset:33792
	ds_read_b128 v[180:183], v230 offset:34816
	ds_read_b128 v[184:187], v230 offset:35840
	ds_read_b128 v[188:191], v230 offset:36864
	ds_read_b128 v[192:195], v230 offset:37888
	ds_read_b128 v[196:199], v230 offset:38912
	ds_read_b128 v[200:203], v230 offset:39936
	global_load_lds_dwordx4 v[214:215], off
	v_lshl_add_u64 v[214:215], s[64:65], 0, v[148:149]
	s_mov_b32 m0, s21
	s_nop 0
	global_load_lds_dwordx4 v[214:215], off
	s_waitcnt vmcnt(8)
	s_waitcnt lgkmcnt(0)
	s_barrier
	v_mfma_f32_16x16x32_bf16 v[142:145], v[64:67], v[172:175], v[142:145]
	v_mfma_f32_16x16x32_bf16 v[138:141], v[72:75], v[172:175], v[138:141]
	v_mfma_f32_16x16x32_bf16 v[134:137], v[64:67], v[180:183], v[134:137]
	v_mfma_f32_16x16x32_bf16 v[124:127], v[72:75], v[180:183], v[124:127]
	v_mfma_f32_16x16x32_bf16 v[108:111], v[64:67], v[188:191], v[108:111]
	v_mfma_f32_16x16x32_bf16 v[104:107], v[72:75], v[188:191], v[104:107]
	v_mfma_f32_16x16x32_bf16 v[100:103], v[64:67], v[196:199], v[100:103]
	v_mfma_f32_16x16x32_bf16 v[92:95], v[72:75], v[196:199], v[92:95]
	v_mfma_f32_16x16x32_bf16 v[142:145], v[68:71], v[176:179], v[142:145]
	v_mfma_f32_16x16x32_bf16 v[138:141], v[76:79], v[176:179], v[138:141]
	v_mfma_f32_16x16x32_bf16 v[134:137], v[68:71], v[184:187], v[134:137]
	v_mfma_f32_16x16x32_bf16 v[124:127], v[76:79], v[184:187], v[124:127]
	v_mfma_f32_16x16x32_bf16 v[108:111], v[68:71], v[192:195], v[108:111]
	v_mfma_f32_16x16x32_bf16 v[104:107], v[76:79], v[192:195], v[104:107]
	v_mfma_f32_16x16x32_bf16 v[100:103], v[68:71], v[200:203], v[100:103]
	v_mfma_f32_16x16x32_bf16 v[92:95], v[76:79], v[200:203], v[92:95]
	v_mfma_f32_16x16x32_bf16 v[130:133], v[156:159], v[172:175], v[130:133]
	v_mfma_f32_16x16x32_bf16 v[120:123], v[164:167], v[172:175], v[120:123]
	v_mfma_f32_16x16x32_bf16 v[116:119], v[156:159], v[180:183], v[116:119]
	v_mfma_f32_16x16x32_bf16 v[112:115], v[164:167], v[180:183], v[112:115]
	v_mfma_f32_16x16x32_bf16 v[96:99], v[156:159], v[188:191], v[96:99]
	v_mfma_f32_16x16x32_bf16 v[88:91], v[164:167], v[188:191], v[88:91]
	v_mfma_f32_16x16x32_bf16 v[84:87], v[156:159], v[196:199], v[84:87]
	v_mfma_f32_16x16x32_bf16 v[80:83], v[164:167], v[196:199], v[80:83]
	v_mfma_f32_16x16x32_bf16 v[130:133], v[160:163], v[176:179], v[130:133]
	v_mfma_f32_16x16x32_bf16 v[120:123], v[168:171], v[176:179], v[120:123]
	v_mfma_f32_16x16x32_bf16 v[116:119], v[160:163], v[184:187], v[116:119]
	v_mfma_f32_16x16x32_bf16 v[112:115], v[168:171], v[184:187], v[112:115]
	v_mfma_f32_16x16x32_bf16 v[96:99], v[160:163], v[192:195], v[96:99]
	v_mfma_f32_16x16x32_bf16 v[88:91], v[168:171], v[192:195], v[88:91]
	v_mfma_f32_16x16x32_bf16 v[84:87], v[160:163], v[200:203], v[84:87]
	v_mfma_f32_16x16x32_bf16 v[80:83], v[168:171], v[200:203], v[80:83]
	s_barrier
; #define PG8_STAGE(bufoff, gbase, voff) do { _Pragma("unroll") for (int _i = 0; _i < 2; ++_i) \
;         __builtin_amdgcn_global_load_lds((const unsigned*)((const char*)(gbase) + (voff)[_i]), (PG8_LAS unsigned*)(lds + (bufoff) + ldsw + _i * 8192), 16, 0, 0); } while (0)
; #define PG8_LDA(dst, b, h) do { _Pragma("unroll") for (int m = 0; m < 4; ++m) _Pragma("unroll") for (int k = 0; k < 2; ++k) dst[m][k] = *(const PG8_LAS bf16x8*)(lds + PG8_SA(b, h) + aoff + m * 2048 + k * 1024); } while (0)
; #define PG8_MMA(ai, bj, At, Bt) do { __builtin_amdgcn_s_setprio(1); _Pragma("unroll") for (int m = 0; m < 4; ++m) _Pragma("unroll") for (int n = 0; n < 2; ++n) _Pragma("unroll") for (int k = 0; k < 2; ++k) \
;         acc[ai][bj][m][n] = __builtin_amdgcn_mfma_f32_16x16x32_bf16(Bt[n][k], At[m][k], acc[ai][bj][m][n], 0, 0, 0); __builtin_amdgcn_s_setprio(0); } while (0)
; #define PG8_WAIT_V(n) asm volatile("s_waitcnt vmcnt(" #n ")" ::: "memory")
; #define PG8_WAIT_L(n) asm volatile("s_waitcnt lgkmcnt(" #n ")" ::: "memory")
; #define PG8_BAR __builtin_amdgcn_s_barrier()
; #define PG8_SCHED __builtin_amdgcn_sched_barrier(0)
; template <class Epi, class Sched, bool ALIGN_EPI = false, bool SP2 = false>
; __device__ __forceinline__ void gemm_phase(PG8_LAS unsigned char* lds, const Gemm g, const Sched& S, const Epi& E) {
;     ...
;             PG8_LDA(At, 1, 1); PG8_STAGE(PG8_SB(1, 0), b3, voffB); PG8_STAGE(PG8_SB(1, 1), b3 + hstep, voffB); PG8_STAGE(PG8_SA(1, 0), a3, voffA);
;             PG8_WAIT_V(8); PG8_WAIT_L(0); PG8_BAR; PG8_MMA(1, 0, At, B0); PG8_MMA(1, 1, At, B1); PG8_BAR; PG8_SCHED;
;     ...
;         }
;         if constexpr (ALIGN_EPI) { if (wr == 0) PG8_BAR; }
	s_add_i32 s64, s84, s17
	v_lshl_add_u64 v[204:205], v[204:205], 0, s[90:91]
	s_mov_b32 m0, s64
	ds_read_b128 v[172:175], v230 offset:49152
	ds_read_b128 v[176:179], v230 offset:50176
	ds_read_b128 v[180:183], v230 offset:51200
	ds_read_b128 v[184:187], v230 offset:52224
	ds_read_b128 v[188:191], v230 offset:53248
	ds_read_b128 v[192:195], v230 offset:54272
	ds_read_b128 v[196:199], v230 offset:55296
	ds_read_b128 v[200:203], v230 offset:56320
	global_load_lds_dwordx4 v[204:205], off
	s_add_i32 m0, s64, 0x2000
	s_add_u32 s58, s58, 0x40080
	v_lshl_add_u64 v[204:205], v[206:207], 0, s[90:91]
	s_addc_u32 s59, s59, 0
	s_add_i32 s64, s85, s17
	global_load_lds_dwordx4 v[204:205], off
	v_lshl_add_u64 v[204:205], s[58:59], 0, v[128:129]
	s_mov_b32 m0, s64
	s_nop 0
	global_load_lds_dwordx4 v[204:205], off
	v_lshl_add_u64 v[204:205], s[58:59], 0, v[146:147]
	s_add_i32 m0, s64, 0x2000
	s_nop 0
	global_load_lds_dwordx4 v[204:205], off
	v_lshl_add_u64 v[204:205], v[208:209], 0, s[90:91]
	s_mov_b32 m0, s28
	s_nop 0
	global_load_lds_dwordx4 v[204:205], off
	v_lshl_add_u64 v[204:205], v[210:211], 0, s[90:91]
	s_mov_b32 m0, s29
	s_nop 0
	global_load_lds_dwordx4 v[204:205], off
	s_waitcnt vmcnt(8)
	s_waitcnt lgkmcnt(0)
	s_barrier
	v_mfma_f32_16x16x32_bf16 v[60:63], v[64:67], v[172:175], v[60:63]
	v_mfma_f32_16x16x32_bf16 v[56:59], v[72:75], v[172:175], v[56:59]
	v_mfma_f32_16x16x32_bf16 v[52:55], v[64:67], v[180:183], v[52:55]
	v_mfma_f32_16x16x32_bf16 v[44:47], v[72:75], v[180:183], v[44:47]
	v_mfma_f32_16x16x32_bf16 v[28:31], v[64:67], v[188:191], v[28:31]
	v_mfma_f32_16x16x32_bf16 v[24:27], v[72:75], v[188:191], v[24:27]
	v_mfma_f32_16x16x32_bf16 v[12:15], v[64:67], v[196:199], v[12:15]
	v_mfma_f32_16x16x32_bf16 v[8:11], v[72:75], v[196:199], v[8:11]
	v_mfma_f32_16x16x32_bf16 v[60:63], v[68:71], v[176:179], v[60:63]
	v_mfma_f32_16x16x32_bf16 v[56:59], v[76:79], v[176:179], v[56:59]
	v_mfma_f32_16x16x32_bf16 v[52:55], v[68:71], v[184:187], v[52:55]
	v_mfma_f32_16x16x32_bf16 v[44:47], v[76:79], v[184:187], v[44:47]
	v_mfma_f32_16x16x32_bf16 v[28:31], v[68:71], v[192:195], v[28:31]
	v_mfma_f32_16x16x32_bf16 v[24:27], v[76:79], v[192:195], v[24:27]
	v_mfma_f32_16x16x32_bf16 v[12:15], v[68:71], v[200:203], v[12:15]
	v_mfma_f32_16x16x32_bf16 v[8:11], v[76:79], v[200:203], v[8:11]
	v_mfma_f32_16x16x32_bf16 v[48:51], v[156:159], v[172:175], v[48:51]
	v_mfma_f32_16x16x32_bf16 v[40:43], v[164:167], v[172:175], v[40:43]
	v_mfma_f32_16x16x32_bf16 v[36:39], v[156:159], v[180:183], v[36:39]
	v_mfma_f32_16x16x32_bf16 v[32:35], v[164:167], v[180:183], v[32:35]
	v_mfma_f32_16x16x32_bf16 v[20:23], v[156:159], v[188:191], v[20:23]
	v_mfma_f32_16x16x32_bf16 v[16:19], v[164:167], v[188:191], v[16:19]
	v_mfma_f32_16x16x32_bf16 v[4:7], v[156:159], v[196:199], v[4:7]
	v_mfma_f32_16x16x32_bf16 v[0:3], v[164:167], v[196:199], v[0:3]
	v_mfma_f32_16x16x32_bf16 v[48:51], v[160:163], v[176:179], v[48:51]
	v_mfma_f32_16x16x32_bf16 v[40:43], v[168:171], v[176:179], v[40:43]
	v_mfma_f32_16x16x32_bf16 v[36:39], v[160:163], v[184:187], v[36:39]
	v_mfma_f32_16x16x32_bf16 v[32:35], v[168:171], v[184:187], v[32:35]
	v_mfma_f32_16x16x32_bf16 v[20:23], v[160:163], v[192:195], v[20:23]
	v_mfma_f32_16x16x32_bf16 v[16:19], v[168:171], v[192:195], v[16:19]
	v_mfma_f32_16x16x32_bf16 v[4:7], v[160:163], v[200:203], v[4:7]
	v_mfma_f32_16x16x32_bf16 v[0:3], v[168:171], v[200:203], v[0:3]
	s_barrier
	s_add_i32 s94, s94, 2
	s_add_u32 vcc_lo, vcc_lo, 0x100
	s_addc_u32 vcc_hi, vcc_hi, 0
	s_add_u32 s88, s88, 0x100
	s_addc_u32 s93, s93, 0
	s_cmp_gt_u32 s94, 13
	s_cbranch_scc0 .LBB0_598
	s_and_b64 vcc, exec, s[72:73]
	s_cbranch_vccz .LBB0_601
	s_barrier

; #define PG8_STAGE(bufoff, gbase, voff) do { _Pragma("unroll") for (int _i = 0; _i < 2; ++_i) \
;         __builtin_amdgcn_global_load_lds((const unsigned*)((const char*)(gbase) + (voff)[_i]), (PG8_LAS unsigned*)(lds + (bufoff) + ldsw + _i * 8192), 16, 0, 0); } while (0)
; #define PG8_LDA(dst, b, h) do { _Pragma("unroll") for (int m = 0; m < 4; ++m) _Pragma("unroll") for (int k = 0; k < 2; ++k) dst[m][k] = *(const PG8_LAS bf16x8*)(lds + PG8_SA(b, h) + aoff + m * 2048 + k * 1024); } while (0)
; #define PG8_LDB(dst, b, h) do { _Pragma("unroll") for (int n = 0; n < 2; ++n) _Pragma("unroll") for (int k = 0; k < 2; ++k) dst[n][k] = *(const PG8_LAS bf16x8*)(lds + PG8_SB(b, h) + boff + n * 2048 + k * 1024); } while (0)
; #define PG8_MMA(ai, bj, At, Bt) do { __builtin_amdgcn_s_setprio(1); _Pragma("unroll") for (int m = 0; m < 4; ++m) _Pragma("unroll") for (int n = 0; n < 2; ++n) _Pragma("unroll") for (int k = 0; k < 2; ++k) \
;         acc[ai][bj][m][n] = __builtin_amdgcn_mfma_f32_16x16x32_bf16(Bt[n][k], At[m][k], acc[ai][bj][m][n], 0, 0, 0); __builtin_amdgcn_s_setprio(0); } while (0)
; #define PG8_WAIT_V(n) asm volatile("s_waitcnt vmcnt(" #n ")" ::: "memory")
; template <class Epi, class Sched, bool ALIGN_EPI = false, bool SP2 = false>
; __device__ __forceinline__ void gemm_phase(PG8_LAS unsigned char* lds, const Gemm g, const Sched& S, const Epi& E) {
;     ...
;         const char* nA = has_next ? (const char*)g.A + (size_t)nxt.pm * tstep : cA; const char* nB = has_next ? (const char*)g.Bt + (size_t)nxt.pn * tstep : cB;
;         for (int t = 0; t < nt; t += 2) {
;             const bool last = (t == nt - 2);
;             const char* a1 = cA + (size_t)(t + 1) * kstep;
;             const char* a2 = last ? nA : cA + (size_t)(t + 2) * kstep; const char* b2 = last ? nB : cB + (size_t)(t + 2) * kstep;
;             const char* a3 = a2 + kstep; const char* b3 = b2 + kstep;
;             if (last && has_next) S.a_ready(nxt);
;             if constexpr (SP2) {
;             PG8_LDB(B0, 0, 0); PG8_LDB(B1, 0, 1); PG8_SCHED; PG8_LDA(At, 0, 0); PG8_STAGE(PG8_SA(1, 1), a1 + hstep, voffA);
;             PG8_WAIT_V(8); PG8_WAIT_L(0); PG8_BAR; PG8_MMA(0, 0, At, B0); PG8_MMA(0, 1, At, B1); PG8_BAR; PG8_SCHED;
;             PG8_LDA(At, 0, 1); PG8_STAGE(PG8_SB(0, 0), b2, voffB); PG8_STAGE(PG8_SB(0, 1), b2 + hstep, voffB); PG8_STAGE(PG8_SA(0, 0), a2, voffA);
.LBB0_813:
	s_add_u32 s8, s66, 0xfffc0080
	s_addc_u32 s37, s67, -1
	s_add_i32 s49, 0, 0x10000
	s_cmp_eq_u32 s36, 12
	s_cselect_b32 s65, s28, s37
	s_cselect_b32 s64, s29, s8
	s_cselect_b32 s59, s30, s35
	s_cselect_b32 s58, s31, s34
	s_add_i32 s8, 0, 0x14000
	v_add_u32_e32 v156, s49, v145
	v_add_u32_e32 v172, s8, v145
	ds_read_b128 v[140:143], v156
	ds_read_b128 v[148:151], v156 offset:1024
	ds_read_b128 v[152:155], v156 offset:2048
	ds_read_b128 v[156:159], v156 offset:3072
	ds_read_b128 v[160:163], v172
	ds_read_b128 v[164:167], v172 offset:1024
	ds_read_b128 v[168:171], v172 offset:2048
	ds_read_b128 v[172:175], v172 offset:3072
	v_lshl_add_u64 v[208:209], s[66:67], 0, v[136:137]
	s_add_i32 m0, s18, 0xc000
	ds_read_b128 v[176:179], v147
	ds_read_b128 v[180:183], v147 offset:1024
	ds_read_b128 v[184:187], v147 offset:2048
	ds_read_b128 v[188:191], v147 offset:3072
	ds_read_b128 v[192:195], v147 offset:4096
	ds_read_b128 v[196:199], v147 offset:5120
	ds_read_b128 v[200:203], v147 offset:6144
	ds_read_b128 v[204:207], v147 offset:7168
	global_load_lds_dwordx4 v[208:209], off
	v_lshl_add_u64 v[208:209], s[66:67], 0, v[138:139]
	s_add_i32 m0, s18, 0xe000
	s_nop 0
	global_load_lds_dwordx4 v[208:209], off
	s_waitcnt vmcnt(8)
	s_waitcnt lgkmcnt(0)
	s_barrier
	v_mfma_f32_16x16x32_bf16 v[124:127], v[140:143], v[176:179], v[124:127]
	v_mfma_f32_16x16x32_bf16 v[116:119], v[152:155], v[176:179], v[116:119]
	v_mfma_f32_16x16x32_bf16 v[108:111], v[140:143], v[184:187], v[108:111]
	v_mfma_f32_16x16x32_bf16 v[100:103], v[152:155], v[184:187], v[100:103]
	v_mfma_f32_16x16x32_bf16 v[92:95], v[140:143], v[192:195], v[92:95]
	v_mfma_f32_16x16x32_bf16 v[84:87], v[152:155], v[192:195], v[84:87]
	v_mfma_f32_16x16x32_bf16 v[76:79], v[140:143], v[200:203], v[76:79]
	v_mfma_f32_16x16x32_bf16 v[68:71], v[152:155], v[200:203], v[68:71]
	v_mfma_f32_16x16x32_bf16 v[124:127], v[148:151], v[180:183], v[124:127]
	v_mfma_f32_16x16x32_bf16 v[116:119], v[156:159], v[180:183], v[116:119]
	v_mfma_f32_16x16x32_bf16 v[108:111], v[148:151], v[188:191], v[108:111]
	v_mfma_f32_16x16x32_bf16 v[100:103], v[156:159], v[188:191], v[100:103]
	v_mfma_f32_16x16x32_bf16 v[92:95], v[148:151], v[196:199], v[92:95]
	v_mfma_f32_16x16x32_bf16 v[84:87], v[156:159], v[196:199], v[84:87]
	v_mfma_f32_16x16x32_bf16 v[76:79], v[148:151], v[204:207], v[76:79]
	v_mfma_f32_16x16x32_bf16 v[68:71], v[156:159], v[204:207], v[68:71]
	v_mfma_f32_16x16x32_bf16 v[120:123], v[160:163], v[176:179], v[120:123]
	v_mfma_f32_16x16x32_bf16 v[112:115], v[168:171], v[176:179], v[112:115]
	v_mfma_f32_16x16x32_bf16 v[104:107], v[160:163], v[184:187], v[104:107]
	v_mfma_f32_16x16x32_bf16 v[96:99], v[168:171], v[184:187], v[96:99]
	v_mfma_f32_16x16x32_bf16 v[88:91], v[160:163], v[192:195], v[88:91]
	v_mfma_f32_16x16x32_bf16 v[80:83], v[168:171], v[192:195], v[80:83]
	v_mfma_f32_16x16x32_bf16 v[72:75], v[160:163], v[200:203], v[72:75]
	v_mfma_f32_16x16x32_bf16 v[64:67], v[168:171], v[200:203], v[64:67]
	v_mfma_f32_16x16x32_bf16 v[120:123], v[164:167], v[180:183], v[120:123]
	v_mfma_f32_16x16x32_bf16 v[112:115], v[172:175], v[180:183], v[112:115]
	v_mfma_f32_16x16x32_bf16 v[104:107], v[164:167], v[188:191], v[104:107]
	v_mfma_f32_16x16x32_bf16 v[96:99], v[172:175], v[188:191], v[96:99]
	v_mfma_f32_16x16x32_bf16 v[88:91], v[164:167], v[196:199], v[88:91]
	v_mfma_f32_16x16x32_bf16 v[80:83], v[172:175], v[196:199], v[80:83]
	v_mfma_f32_16x16x32_bf16 v[72:75], v[164:167], v[204:207], v[72:75]
	v_mfma_f32_16x16x32_bf16 v[64:67], v[172:175], v[204:207], v[64:67]
	s_barrier
	s_add_i32 s37, s49, s17
	v_lshl_add_u64 v[208:209], s[58:59], 0, v[128:129]
	s_mov_b32 m0, s37
	ds_read_b128 v[176:179], v147 offset:16384
	ds_read_b128 v[180:183], v147 offset:17408
	ds_read_b128 v[184:187], v147 offset:18432
	ds_read_b128 v[188:191], v147 offset:19456
	ds_read_b128 v[192:195], v147 offset:20480
	ds_read_b128 v[196:199], v147 offset:21504
	ds_read_b128 v[200:203], v147 offset:22528
	ds_read_b128 v[204:207], v147 offset:23552
	global_load_lds_dwordx4 v[208:209], off
	s_add_i32 m0, s37, 0x2000
	s_add_u32 s72, s58, 0x40000
	v_lshl_add_u64 v[210:211], s[58:59], 0, v[130:131]
	s_addc_u32 s73, s59, 0
	s_add_i32 s8, s8, s17
	global_load_lds_dwordx4 v[210:211], off
	v_lshl_add_u64 v[214:215], s[72:73], 0, v[128:129]
	s_mov_b32 m0, s8
	v_lshl_add_u64 v[222:223], s[64:65], 0, v[132:133]
	global_load_lds_dwordx4 v[214:215], off
	v_lshl_add_u64 v[214:215], s[72:73], 0, v[130:131]
	s_add_i32 m0, s8, 0x2000
	s_nop 0
	global_load_lds_dwordx4 v[214:215], off
	v_lshl_add_u64 v[214:215], s[64:65], 0, v[134:135]
	s_mov_b32 m0, s18
	s_nop 0
	global_load_lds_dwordx4 v[214:215], off
	s_mov_b32 m0, s19
	s_nop 0
	global_load_lds_dwordx4 v[222:223], off
	s_waitcnt vmcnt(8)
	s_waitcnt lgkmcnt(0)
	s_barrier
; #define PG8_STAGE(bufoff, gbase, voff) do { _Pragma("unroll") for (int _i = 0; _i < 2; ++_i) \
;         __builtin_amdgcn_global_load_lds((const unsigned*)((const char*)(gbase) + (voff)[_i]), (PG8_LAS unsigned*)(lds + (bufoff) + ldsw + _i * 8192), 16, 0, 0); } while (0)
; #define PG8_LDA(dst, b, h) do { _Pragma("unroll") for (int m = 0; m < 4; ++m) _Pragma("unroll") for (int k = 0; k < 2; ++k) dst[m][k] = *(const PG8_LAS bf16x8*)(lds + PG8_SA(b, h) + aoff + m * 2048 + k * 1024); } while (0)
; #define PG8_LDB(dst, b, h) do { _Pragma("unroll") for (int n = 0; n < 2; ++n) _Pragma("unroll") for (int k = 0; k < 2; ++k) dst[n][k] = *(const PG8_LAS bf16x8*)(lds + PG8_SB(b, h) + boff + n * 2048 + k * 1024); } while (0)
; #define PG8_MMA(ai, bj, At, Bt) do { __builtin_amdgcn_s_setprio(1); _Pragma("unroll") for (int m = 0; m < 4; ++m) _Pragma("unroll") for (int n = 0; n < 2; ++n) _Pragma("unroll") for (int k = 0; k < 2; ++k) \
;         acc[ai][bj][m][n] = __builtin_amdgcn_mfma_f32_16x16x32_bf16(Bt[n][k], At[m][k], acc[ai][bj][m][n], 0, 0, 0); __builtin_amdgcn_s_setprio(0); } while (0)
; #define PG8_WAIT_V(n) asm volatile("s_waitcnt vmcnt(" #n ")" ::: "memory")
; #define PG8_WAIT_L(n) asm volatile("s_waitcnt lgkmcnt(" #n ")" ::: "memory")
; #define PG8_BAR __builtin_amdgcn_s_barrier()
; #define PG8_SCHED __builtin_amdgcn_sched_barrier(0)
; template <class Epi, class Sched, bool ALIGN_EPI = false, bool SP2 = false>
; __device__ __forceinline__ void gemm_phase(PG8_LAS unsigned char* lds, const Gemm g, const Sched& S, const Epi& E) {
;     ...
;             PG8_WAIT_V(8); PG8_WAIT_L(0); PG8_BAR; PG8_MMA(1, 0, At, B0); PG8_MMA(1, 1, At, B1); PG8_BAR; PG8_SCHED;
;             PG8_LDB(B0, 1, 0); PG8_LDB(B1, 1, 1); PG8_SCHED; PG8_LDA(At, 1, 0); PG8_STAGE(PG8_SA(0, 1), a2 + hstep, voffA);
;             PG8_WAIT_V(8); PG8_WAIT_L(0); PG8_BAR; PG8_MMA(0, 0, At, B0); PG8_MMA(0, 1, At, B1); PG8_BAR; PG8_SCHED;
	v_mfma_f32_16x16x32_bf16 v[60:63], v[140:143], v[176:179], v[60:63]
	v_mfma_f32_16x16x32_bf16 v[52:55], v[152:155], v[176:179], v[52:55]
	v_mfma_f32_16x16x32_bf16 v[44:47], v[140:143], v[184:187], v[44:47]
	v_mfma_f32_16x16x32_bf16 v[36:39], v[152:155], v[184:187], v[36:39]
	v_mfma_f32_16x16x32_bf16 v[28:31], v[140:143], v[192:195], v[28:31]
	v_mfma_f32_16x16x32_bf16 v[20:23], v[152:155], v[192:195], v[20:23]
	v_mfma_f32_16x16x32_bf16 v[12:15], v[140:143], v[200:203], v[12:15]
	v_mfma_f32_16x16x32_bf16 v[4:7], v[152:155], v[200:203], v[4:7]
	v_mfma_f32_16x16x32_bf16 v[60:63], v[148:151], v[180:183], v[60:63]
	v_mfma_f32_16x16x32_bf16 v[52:55], v[156:159], v[180:183], v[52:55]
	v_mfma_f32_16x16x32_bf16 v[44:47], v[148:151], v[188:191], v[44:47]
	v_mfma_f32_16x16x32_bf16 v[36:39], v[156:159], v[188:191], v[36:39]
	v_mfma_f32_16x16x32_bf16 v[28:31], v[148:151], v[196:199], v[28:31]
	v_mfma_f32_16x16x32_bf16 v[20:23], v[156:159], v[196:199], v[20:23]
	v_mfma_f32_16x16x32_bf16 v[12:15], v[148:151], v[204:207], v[12:15]
	v_mfma_f32_16x16x32_bf16 v[4:7], v[156:159], v[204:207], v[4:7]
	v_mfma_f32_16x16x32_bf16 v[56:59], v[160:163], v[176:179], v[56:59]
	v_mfma_f32_16x16x32_bf16 v[48:51], v[168:171], v[176:179], v[48:51]
	v_mfma_f32_16x16x32_bf16 v[40:43], v[160:163], v[184:187], v[40:43]
	v_mfma_f32_16x16x32_bf16 v[32:35], v[168:171], v[184:187], v[32:35]
	v_mfma_f32_16x16x32_bf16 v[24:27], v[160:163], v[192:195], v[24:27]
	v_mfma_f32_16x16x32_bf16 v[16:19], v[168:171], v[192:195], v[16:19]
	v_mfma_f32_16x16x32_bf16 v[8:11], v[160:163], v[200:203], v[8:11]
	v_mfma_f32_16x16x32_bf16 v[0:3], v[168:171], v[200:203], v[0:3]
	v_mfma_f32_16x16x32_bf16 v[56:59], v[164:167], v[180:183], v[56:59]
	v_mfma_f32_16x16x32_bf16 v[48:51], v[172:175], v[180:183], v[48:51]
	v_mfma_f32_16x16x32_bf16 v[40:43], v[164:167], v[188:191], v[40:43]
	v_mfma_f32_16x16x32_bf16 v[32:35], v[172:175], v[188:191], v[32:35]
	v_mfma_f32_16x16x32_bf16 v[24:27], v[164:167], v[196:199], v[24:27]
	v_mfma_f32_16x16x32_bf16 v[16:19], v[172:175], v[196:199], v[16:19]
	v_mfma_f32_16x16x32_bf16 v[8:11], v[164:167], v[204:207], v[8:11]
	v_mfma_f32_16x16x32_bf16 v[0:3], v[172:175], v[204:207], v[0:3]
	s_barrier
	s_add_i32 s8, 0, 0x18000
	s_add_i32 s37, 0, 0x1c000
	v_add_u32_e32 v156, s8, v145
	v_add_u32_e32 v172, s37, v145
	ds_read_b128 v[140:143], v156
	ds_read_b128 v[148:151], v156 offset:1024
	ds_read_b128 v[152:155], v156 offset:2048
	ds_read_b128 v[156:159], v156 offset:3072
	ds_read_b128 v[160:163], v172
	ds_read_b128 v[164:167], v172 offset:1024
	ds_read_b128 v[168:171], v172 offset:2048
	ds_read_b128 v[172:175], v172 offset:3072
	s_add_u32 s64, s64, 0x40000
	s_addc_u32 s65, s65, 0
	s_mov_b32 m0, s20
	v_lshl_add_u64 v[228:229], s[64:65], 0, v[134:135]
	ds_read_b128 v[176:179], v147 offset:32768
	ds_read_b128 v[180:183], v147 offset:33792
	ds_read_b128 v[184:187], v147 offset:34816
	ds_read_b128 v[188:191], v147 offset:35840
	ds_read_b128 v[192:195], v147 offset:36864
	ds_read_b128 v[196:199], v147 offset:37888
	ds_read_b128 v[200:203], v147 offset:38912
	ds_read_b128 v[204:207], v147 offset:39936
	global_load_lds_dwordx4 v[228:229], off
	v_lshl_add_u64 v[228:229], s[64:65], 0, v[132:133]
	s_mov_b32 m0, s21
	s_nop 0
	global_load_lds_dwordx4 v[228:229], off
	s_waitcnt vmcnt(8)
	s_waitcnt lgkmcnt(0)
	s_barrier
	v_mfma_f32_16x16x32_bf16 v[124:127], v[140:143], v[176:179], v[124:127]
	v_mfma_f32_16x16x32_bf16 v[116:119], v[152:155], v[176:179], v[116:119]
	v_mfma_f32_16x16x32_bf16 v[108:111], v[140:143], v[184:187], v[108:111]
	v_mfma_f32_16x16x32_bf16 v[100:103], v[152:155], v[184:187], v[100:103]
	v_mfma_f32_16x16x32_bf16 v[92:95], v[140:143], v[192:195], v[92:95]
	v_mfma_f32_16x16x32_bf16 v[84:87], v[152:155], v[192:195], v[84:87]
	v_mfma_f32_16x16x32_bf16 v[76:79], v[140:143], v[200:203], v[76:79]
	v_mfma_f32_16x16x32_bf16 v[68:71], v[152:155], v[200:203], v[68:71]
	v_mfma_f32_16x16x32_bf16 v[124:127], v[148:151], v[180:183], v[124:127]
	v_mfma_f32_16x16x32_bf16 v[116:119], v[156:159], v[180:183], v[116:119]
	v_mfma_f32_16x16x32_bf16 v[108:111], v[148:151], v[188:191], v[108:111]
	v_mfma_f32_16x16x32_bf16 v[100:103], v[156:159], v[188:191], v[100:103]
	v_mfma_f32_16x16x32_bf16 v[92:95], v[148:151], v[196:199], v[92:95]
	v_mfma_f32_16x16x32_bf16 v[84:87], v[156:159], v[196:199], v[84:87]
	v_mfma_f32_16x16x32_bf16 v[76:79], v[148:151], v[204:207], v[76:79]
	v_mfma_f32_16x16x32_bf16 v[68:71], v[156:159], v[204:207], v[68:71]
	v_mfma_f32_16x16x32_bf16 v[120:123], v[160:163], v[176:179], v[120:123]
	v_mfma_f32_16x16x32_bf16 v[112:115], v[168:171], v[176:179], v[112:115]
	v_mfma_f32_16x16x32_bf16 v[104:107], v[160:163], v[184:187], v[104:107]
	v_mfma_f32_16x16x32_bf16 v[96:99], v[168:171], v[184:187], v[96:99]
	v_mfma_f32_16x16x32_bf16 v[88:91], v[160:163], v[192:195], v[88:91]
	v_mfma_f32_16x16x32_bf16 v[80:83], v[168:171], v[192:195], v[80:83]
	v_mfma_f32_16x16x32_bf16 v[72:75], v[160:163], v[200:203], v[72:75]
	v_mfma_f32_16x16x32_bf16 v[64:67], v[168:171], v[200:203], v[64:67]
	v_mfma_f32_16x16x32_bf16 v[120:123], v[164:167], v[180:183], v[120:123]
	v_mfma_f32_16x16x32_bf16 v[112:115], v[172:175], v[180:183], v[112:115]
	v_mfma_f32_16x16x32_bf16 v[104:107], v[164:167], v[188:191], v[104:107]
	v_mfma_f32_16x16x32_bf16 v[96:99], v[172:175], v[188:191], v[96:99]
	v_mfma_f32_16x16x32_bf16 v[88:91], v[164:167], v[196:199], v[88:91]
	v_mfma_f32_16x16x32_bf16 v[80:83], v[172:175], v[196:199], v[80:83]
	v_mfma_f32_16x16x32_bf16 v[72:75], v[164:167], v[204:207], v[72:75]
	v_mfma_f32_16x16x32_bf16 v[64:67], v[172:175], v[204:207], v[64:67]
	s_barrier
; #define PG8_STAGE(bufoff, gbase, voff) do { _Pragma("unroll") for (int _i = 0; _i < 2; ++_i) \
;         __builtin_amdgcn_global_load_lds((const unsigned*)((const char*)(gbase) + (voff)[_i]), (PG8_LAS unsigned*)(lds + (bufoff) + ldsw + _i * 8192), 16, 0, 0); } while (0)
; #define PG8_LDA(dst, b, h) do { _Pragma("unroll") for (int m = 0; m < 4; ++m) _Pragma("unroll") for (int k = 0; k < 2; ++k) dst[m][k] = *(const PG8_LAS bf16x8*)(lds + PG8_SA(b, h) + aoff + m * 2048 + k * 1024); } while (0)
; #define PG8_MMA(ai, bj, At, Bt) do { __builtin_amdgcn_s_setprio(1); _Pragma("unroll") for (int m = 0; m < 4; ++m) _Pragma("unroll") for (int n = 0; n < 2; ++n) _Pragma("unroll") for (int k = 0; k < 2; ++k) \
;         acc[ai][bj][m][n] = __builtin_amdgcn_mfma_f32_16x16x32_bf16(Bt[n][k], At[m][k], acc[ai][bj][m][n], 0, 0, 0); __builtin_amdgcn_s_setprio(0); } while (0)
; #define PG8_WAIT_V(n) asm volatile("s_waitcnt vmcnt(" #n ")" ::: "memory")
; #define PG8_WAIT_L(n) asm volatile("s_waitcnt lgkmcnt(" #n ")" ::: "memory")
; #define PG8_BAR __builtin_amdgcn_s_barrier()
; #define PG8_SCHED __builtin_amdgcn_sched_barrier(0)
; template <class Epi, class Sched, bool ALIGN_EPI = false, bool SP2 = false>
; __device__ __forceinline__ void gemm_phase(PG8_LAS unsigned char* lds, const Gemm g, const Sched& S, const Epi& E) {
;     ...
;             PG8_LDA(At, 1, 1); PG8_STAGE(PG8_SB(1, 0), b3, voffB); PG8_STAGE(PG8_SB(1, 1), b3 + hstep, voffB); PG8_STAGE(PG8_SA(1, 0), a3, voffA);
;             PG8_WAIT_V(8); PG8_WAIT_L(0); PG8_BAR; PG8_MMA(1, 0, At, B0); PG8_MMA(1, 1, At, B1); PG8_BAR; PG8_SCHED;
;     ...
;         }
;         if constexpr (ALIGN_EPI) { if (wr == 0) PG8_BAR; }
	s_add_i32 s8, s8, s17
	v_lshl_add_u64 v[208:209], v[208:209], 0, s[90:91]
	s_mov_b32 m0, s8
	ds_read_b128 v[176:179], v147 offset:49152
	ds_read_b128 v[180:183], v147 offset:50176
	ds_read_b128 v[184:187], v147 offset:51200
	ds_read_b128 v[188:191], v147 offset:52224
	ds_read_b128 v[192:195], v147 offset:53248
	ds_read_b128 v[196:199], v147 offset:54272
	ds_read_b128 v[200:203], v147 offset:55296
	ds_read_b128 v[204:207], v147 offset:56320
	global_load_lds_dwordx4 v[208:209], off
	s_add_i32 m0, s8, 0x2000
	s_add_u32 s58, s58, 0x40080
	v_lshl_add_u64 v[208:209], v[210:211], 0, s[90:91]
	s_addc_u32 s59, s59, 0
	s_add_i32 s8, s37, s17
	global_load_lds_dwordx4 v[208:209], off
	v_lshl_add_u64 v[208:209], s[58:59], 0, v[128:129]
	s_mov_b32 m0, s8
	s_nop 0
	global_load_lds_dwordx4 v[208:209], off
	v_lshl_add_u64 v[208:209], s[58:59], 0, v[130:131]
	s_add_i32 m0, s8, 0x2000
	s_nop 0
	global_load_lds_dwordx4 v[208:209], off
	v_lshl_add_u64 v[208:209], v[214:215], 0, s[90:91]
	s_mov_b32 m0, s22
	s_nop 0
	global_load_lds_dwordx4 v[208:209], off
	v_lshl_add_u64 v[208:209], v[222:223], 0, s[90:91]
	s_mov_b32 m0, s23
	s_nop 0
	global_load_lds_dwordx4 v[208:209], off
	s_waitcnt vmcnt(8)
	s_waitcnt lgkmcnt(0)
	s_barrier
	v_mfma_f32_16x16x32_bf16 v[60:63], v[140:143], v[176:179], v[60:63]
	v_mfma_f32_16x16x32_bf16 v[52:55], v[152:155], v[176:179], v[52:55]
	v_mfma_f32_16x16x32_bf16 v[44:47], v[140:143], v[184:187], v[44:47]
	v_mfma_f32_16x16x32_bf16 v[36:39], v[152:155], v[184:187], v[36:39]
	v_mfma_f32_16x16x32_bf16 v[28:31], v[140:143], v[192:195], v[28:31]
	v_mfma_f32_16x16x32_bf16 v[20:23], v[152:155], v[192:195], v[20:23]
	v_mfma_f32_16x16x32_bf16 v[12:15], v[140:143], v[200:203], v[12:15]
	v_mfma_f32_16x16x32_bf16 v[4:7], v[152:155], v[200:203], v[4:7]
	v_mfma_f32_16x16x32_bf16 v[60:63], v[148:151], v[180:183], v[60:63]
	v_mfma_f32_16x16x32_bf16 v[52:55], v[156:159], v[180:183], v[52:55]
	v_mfma_f32_16x16x32_bf16 v[44:47], v[148:151], v[188:191], v[44:47]
	v_mfma_f32_16x16x32_bf16 v[36:39], v[156:159], v[188:191], v[36:39]
	v_mfma_f32_16x16x32_bf16 v[28:31], v[148:151], v[196:199], v[28:31]
	v_mfma_f32_16x16x32_bf16 v[20:23], v[156:159], v[196:199], v[20:23]
	v_mfma_f32_16x16x32_bf16 v[12:15], v[148:151], v[204:207], v[12:15]
	v_mfma_f32_16x16x32_bf16 v[4:7], v[156:159], v[204:207], v[4:7]
	v_mfma_f32_16x16x32_bf16 v[56:59], v[160:163], v[176:179], v[56:59]
	v_mfma_f32_16x16x32_bf16 v[48:51], v[168:171], v[176:179], v[48:51]
	v_mfma_f32_16x16x32_bf16 v[40:43], v[160:163], v[184:187], v[40:43]
	v_mfma_f32_16x16x32_bf16 v[32:35], v[168:171], v[184:187], v[32:35]
	v_mfma_f32_16x16x32_bf16 v[24:27], v[160:163], v[192:195], v[24:27]
	v_mfma_f32_16x16x32_bf16 v[16:19], v[168:171], v[192:195], v[16:19]
	v_mfma_f32_16x16x32_bf16 v[8:11], v[160:163], v[200:203], v[8:11]
	v_mfma_f32_16x16x32_bf16 v[0:3], v[168:171], v[200:203], v[0:3]
	v_mfma_f32_16x16x32_bf16 v[56:59], v[164:167], v[180:183], v[56:59]
	v_mfma_f32_16x16x32_bf16 v[48:51], v[172:175], v[180:183], v[48:51]
	v_mfma_f32_16x16x32_bf16 v[40:43], v[164:167], v[188:191], v[40:43]
	v_mfma_f32_16x16x32_bf16 v[32:35], v[172:175], v[188:191], v[32:35]
	v_mfma_f32_16x16x32_bf16 v[24:27], v[164:167], v[196:199], v[24:27]
	v_mfma_f32_16x16x32_bf16 v[16:19], v[172:175], v[196:199], v[16:19]
	v_mfma_f32_16x16x32_bf16 v[8:11], v[164:167], v[204:207], v[8:11]
	v_mfma_f32_16x16x32_bf16 v[0:3], v[172:175], v[204:207], v[0:3]
	s_barrier
	s_add_i32 s36, s36, 2
	s_add_u32 s66, s66, 0x100
	s_addc_u32 s67, s67, 0
	s_add_u32 s34, s34, 0x100
	s_addc_u32 s35, s35, 0
	s_cmp_gt_u32 s36, 13
	s_cbranch_scc0 .LBB0_813
	s_and_b64 vcc, exec, s[46:47]
	s_cbranch_vccz .LBB0_816
	s_barrier

; #define PG8_STAGE(bufoff, gbase, voff) do { _Pragma("unroll") for (int _i = 0; _i < 2; ++_i) \
;         __builtin_amdgcn_global_load_lds((const unsigned*)((const char*)(gbase) + (voff)[_i]), (PG8_LAS unsigned*)(lds + (bufoff) + ldsw + _i * 8192), 16, 0, 0); } while (0)
; #define PG8_LDA(dst, b, h) do { _Pragma("unroll") for (int m = 0; m < 4; ++m) _Pragma("unroll") for (int k = 0; k < 2; ++k) dst[m][k] = *(const PG8_LAS bf16x8*)(lds + PG8_SA(b, h) + aoff + m * 2048 + k * 1024); } while (0)
; #define PG8_LDB(dst, b, h) do { _Pragma("unroll") for (int n = 0; n < 2; ++n) _Pragma("unroll") for (int k = 0; k < 2; ++k) dst[n][k] = *(const PG8_LAS bf16x8*)(lds + PG8_SB(b, h) + boff + n * 2048 + k * 1024); } while (0)
; #define PG8_MMA(ai, bj, At, Bt) do { __builtin_amdgcn_s_setprio(1); _Pragma("unroll") for (int m = 0; m < 4; ++m) _Pragma("unroll") for (int n = 0; n < 2; ++n) _Pragma("unroll") for (int k = 0; k < 2; ++k) \
;         acc[ai][bj][m][n] = __builtin_amdgcn_mfma_f32_16x16x32_bf16(Bt[n][k], At[m][k], acc[ai][bj][m][n], 0, 0, 0); __builtin_amdgcn_s_setprio(0); } while (0)
; #define PG8_WAIT_V(n) asm volatile("s_waitcnt vmcnt(" #n ")" ::: "memory")
; template <class Epi, class Sched, bool ALIGN_EPI = false, bool SP2 = false>
; __device__ __forceinline__ void gemm_phase(PG8_LAS unsigned char* lds, const Gemm g, const Sched& S, const Epi& E) {
;     ...
;         const char* nA = has_next ? (const char*)g.A + (size_t)nxt.pm * tstep : cA; const char* nB = has_next ? (const char*)g.Bt + (size_t)nxt.pn * tstep : cB;
;         for (int t = 0; t < nt; t += 2) {
;             const bool last = (t == nt - 2);
;             const char* a1 = cA + (size_t)(t + 1) * kstep;
;             const char* a2 = last ? nA : cA + (size_t)(t + 2) * kstep; const char* b2 = last ? nB : cB + (size_t)(t + 2) * kstep;
;             const char* a3 = a2 + kstep; const char* b3 = b2 + kstep;
;             if (last && has_next) S.a_ready(nxt);
;             if constexpr (SP2) {
;             PG8_LDB(B0, 0, 0); PG8_LDB(B1, 0, 1); PG8_SCHED; PG8_LDA(At, 0, 0); PG8_STAGE(PG8_SA(1, 1), a1 + hstep, voffA);
;             PG8_WAIT_V(8); PG8_WAIT_L(0); PG8_BAR; PG8_MMA(0, 0, At, B0); PG8_MMA(0, 1, At, B1); PG8_BAR; PG8_SCHED;
;             PG8_LDA(At, 0, 1); PG8_STAGE(PG8_SB(0, 0), b2, voffB); PG8_STAGE(PG8_SB(0, 1), b2 + hstep, voffB); PG8_STAGE(PG8_SA(0, 0), a2, voffA);
.LBB0_957:
	s_add_u32 s44, s96, 0x100
	s_addc_u32 s45, s97, 0
	s_add_i32 s8, 0, 0x10000
	s_cmp_eq_u32 s70, 40
	s_cselect_b32 s65, s67, s45
	s_cselect_b32 s64, s66, s44
	s_cselect_b32 s47, s73, s37
	s_cselect_b32 s46, s72, s36
	s_add_i32 s88, 0, 0x14000
	v_add_u32_e32 v142, s8, v185
	v_add_u32_e32 v168, s88, v185
	ds_read_b128 v[130:133], v142
	ds_read_b128 v[134:137], v142 offset:1024
	ds_read_b128 v[138:141], v142 offset:2048
	ds_read_b128 v[142:145], v142 offset:3072
	ds_read_b128 v[156:159], v168
	ds_read_b128 v[160:163], v168 offset:1024
	ds_read_b128 v[164:167], v168 offset:2048
	ds_read_b128 v[168:171], v168 offset:3072
	v_lshl_add_u64 v[208:209], s[96:97], 0, v[152:153]
	s_add_i32 m0, s15, 0xc000
	ds_read_b128 v[172:175], v191
	ds_read_b128 v[176:179], v191 offset:1024
	ds_read_b128 v[180:183], v191 offset:2048
	ds_read_b128 v[186:189], v191 offset:3072
	ds_read_b128 v[192:195], v191 offset:4096
	ds_read_b128 v[196:199], v191 offset:5120
	ds_read_b128 v[200:203], v191 offset:6144
	ds_read_b128 v[204:207], v191 offset:7168
	global_load_lds_dwordx4 v[208:209], off
	v_lshl_add_u64 v[208:209], s[96:97], 0, v[154:155]
	s_add_i32 m0, s15, 0xe000
	s_nop 0
	global_load_lds_dwordx4 v[208:209], off
	s_waitcnt vmcnt(8)
	s_waitcnt lgkmcnt(0)
	s_barrier
	v_mfma_f32_16x16x32_bf16 v[124:127], v[130:133], v[172:175], v[124:127]
	v_mfma_f32_16x16x32_bf16 v[120:123], v[138:141], v[172:175], v[120:123]
	v_mfma_f32_16x16x32_bf16 v[108:111], v[130:133], v[180:183], v[108:111]
	v_mfma_f32_16x16x32_bf16 v[104:107], v[138:141], v[180:183], v[104:107]
	v_mfma_f32_16x16x32_bf16 v[92:95], v[130:133], v[192:195], v[92:95]
	v_mfma_f32_16x16x32_bf16 v[88:91], v[138:141], v[192:195], v[88:91]
	v_mfma_f32_16x16x32_bf16 v[76:79], v[130:133], v[200:203], v[76:79]
	v_mfma_f32_16x16x32_bf16 v[72:75], v[138:141], v[200:203], v[72:75]
	v_mfma_f32_16x16x32_bf16 v[124:127], v[134:137], v[176:179], v[124:127]
	v_mfma_f32_16x16x32_bf16 v[120:123], v[142:145], v[176:179], v[120:123]
	v_mfma_f32_16x16x32_bf16 v[108:111], v[134:137], v[186:189], v[108:111]
	v_mfma_f32_16x16x32_bf16 v[104:107], v[142:145], v[186:189], v[104:107]
	v_mfma_f32_16x16x32_bf16 v[92:95], v[134:137], v[196:199], v[92:95]
	v_mfma_f32_16x16x32_bf16 v[88:91], v[142:145], v[196:199], v[88:91]
	v_mfma_f32_16x16x32_bf16 v[76:79], v[134:137], v[204:207], v[76:79]
	v_mfma_f32_16x16x32_bf16 v[72:75], v[142:145], v[204:207], v[72:75]
	v_mfma_f32_16x16x32_bf16 v[116:119], v[156:159], v[172:175], v[116:119]
	v_mfma_f32_16x16x32_bf16 v[112:115], v[164:167], v[172:175], v[112:115]
	v_mfma_f32_16x16x32_bf16 v[100:103], v[156:159], v[180:183], v[100:103]
	v_mfma_f32_16x16x32_bf16 v[96:99], v[164:167], v[180:183], v[96:99]
	v_mfma_f32_16x16x32_bf16 v[84:87], v[156:159], v[192:195], v[84:87]
	v_mfma_f32_16x16x32_bf16 v[80:83], v[164:167], v[192:195], v[80:83]
	v_mfma_f32_16x16x32_bf16 v[68:71], v[156:159], v[200:203], v[68:71]
	v_mfma_f32_16x16x32_bf16 v[64:67], v[164:167], v[200:203], v[64:67]
	v_mfma_f32_16x16x32_bf16 v[116:119], v[160:163], v[176:179], v[116:119]
	v_mfma_f32_16x16x32_bf16 v[112:115], v[168:171], v[176:179], v[112:115]
	v_mfma_f32_16x16x32_bf16 v[100:103], v[160:163], v[186:189], v[100:103]
	v_mfma_f32_16x16x32_bf16 v[96:99], v[168:171], v[186:189], v[96:99]
	v_mfma_f32_16x16x32_bf16 v[84:87], v[160:163], v[196:199], v[84:87]
	v_mfma_f32_16x16x32_bf16 v[80:83], v[168:171], v[196:199], v[80:83]
	v_mfma_f32_16x16x32_bf16 v[68:71], v[160:163], v[204:207], v[68:71]
	v_mfma_f32_16x16x32_bf16 v[64:67], v[168:171], v[204:207], v[64:67]
	s_barrier
	s_add_i32 s8, s8, s14
	v_lshl_add_u64 v[208:209], s[46:47], 0, v[128:129]
	s_mov_b32 m0, s8
	ds_read_b128 v[172:175], v191 offset:16384
	ds_read_b128 v[176:179], v191 offset:17408
	ds_read_b128 v[180:183], v191 offset:18432
	ds_read_b128 v[186:189], v191 offset:19456
	ds_read_b128 v[192:195], v191 offset:20480
	ds_read_b128 v[196:199], v191 offset:21504
	ds_read_b128 v[200:203], v191 offset:22528
	ds_read_b128 v[204:207], v191 offset:23552
	global_load_lds_dwordx4 v[208:209], off
	s_add_i32 m0, s8, 0x2000
	s_add_u32 s84, s46, 0xb0000
	v_lshl_add_u64 v[210:211], s[46:47], 0, v[146:147]
	s_addc_u32 s85, s47, 0
	s_add_i32 s8, s88, s14
	global_load_lds_dwordx4 v[210:211], off
	v_lshl_add_u64 v[214:215], s[84:85], 0, v[128:129]
	s_mov_b32 m0, s8
	v_lshl_add_u64 v[222:223], s[64:65], 0, v[148:149]
	global_load_lds_dwordx4 v[214:215], off
	v_lshl_add_u64 v[214:215], s[84:85], 0, v[146:147]
	s_add_i32 m0, s8, 0x2000
	s_nop 0
	global_load_lds_dwordx4 v[214:215], off
	v_lshl_add_u64 v[214:215], s[64:65], 0, v[150:151]
	s_mov_b32 m0, s15
	s_nop 0
	global_load_lds_dwordx4 v[214:215], off
	s_mov_b32 m0, s18
	s_nop 0
	global_load_lds_dwordx4 v[222:223], off
	s_waitcnt vmcnt(8)
	s_waitcnt lgkmcnt(0)
	s_barrier
; #define PG8_STAGE(bufoff, gbase, voff) do { _Pragma("unroll") for (int _i = 0; _i < 2; ++_i) \
;         __builtin_amdgcn_global_load_lds((const unsigned*)((const char*)(gbase) + (voff)[_i]), (PG8_LAS unsigned*)(lds + (bufoff) + ldsw + _i * 8192), 16, 0, 0); } while (0)
; #define PG8_LDA(dst, b, h) do { _Pragma("unroll") for (int m = 0; m < 4; ++m) _Pragma("unroll") for (int k = 0; k < 2; ++k) dst[m][k] = *(const PG8_LAS bf16x8*)(lds + PG8_SA(b, h) + aoff + m * 2048 + k * 1024); } while (0)
; #define PG8_LDB(dst, b, h) do { _Pragma("unroll") for (int n = 0; n < 2; ++n) _Pragma("unroll") for (int k = 0; k < 2; ++k) dst[n][k] = *(const PG8_LAS bf16x8*)(lds + PG8_SB(b, h) + boff + n * 2048 + k * 1024); } while (0)
; #define PG8_MMA(ai, bj, At, Bt) do { __builtin_amdgcn_s_setprio(1); _Pragma("unroll") for (int m = 0; m < 4; ++m) _Pragma("unroll") for (int n = 0; n < 2; ++n) _Pragma("unroll") for (int k = 0; k < 2; ++k) \
;         acc[ai][bj][m][n] = __builtin_amdgcn_mfma_f32_16x16x32_bf16(Bt[n][k], At[m][k], acc[ai][bj][m][n], 0, 0, 0); __builtin_amdgcn_s_setprio(0); } while (0)
; #define PG8_WAIT_V(n) asm volatile("s_waitcnt vmcnt(" #n ")" ::: "memory")
; #define PG8_WAIT_L(n) asm volatile("s_waitcnt lgkmcnt(" #n ")" ::: "memory")
; #define PG8_BAR __builtin_amdgcn_s_barrier()
; #define PG8_SCHED __builtin_amdgcn_sched_barrier(0)
; template <class Epi, class Sched, bool ALIGN_EPI = false, bool SP2 = false>
; __device__ __forceinline__ void gemm_phase(PG8_LAS unsigned char* lds, const Gemm g, const Sched& S, const Epi& E) {
;     ...
;             PG8_WAIT_V(8); PG8_WAIT_L(0); PG8_BAR; PG8_MMA(1, 0, At, B0); PG8_MMA(1, 1, At, B1); PG8_BAR; PG8_SCHED;
;             PG8_LDB(B0, 1, 0); PG8_LDB(B1, 1, 1); PG8_SCHED; PG8_LDA(At, 1, 0); PG8_STAGE(PG8_SA(0, 1), a2 + hstep, voffA);
;             PG8_WAIT_V(8); PG8_WAIT_L(0); PG8_BAR; PG8_MMA(0, 0, At, B0); PG8_MMA(0, 1, At, B1); PG8_BAR; PG8_SCHED;
	v_mfma_f32_16x16x32_bf16 v[60:63], v[130:133], v[172:175], v[60:63]
	v_mfma_f32_16x16x32_bf16 v[56:59], v[138:141], v[172:175], v[56:59]
	v_mfma_f32_16x16x32_bf16 v[44:47], v[130:133], v[180:183], v[44:47]
	v_mfma_f32_16x16x32_bf16 v[40:43], v[138:141], v[180:183], v[40:43]
	v_mfma_f32_16x16x32_bf16 v[28:31], v[130:133], v[192:195], v[28:31]
	v_mfma_f32_16x16x32_bf16 v[24:27], v[138:141], v[192:195], v[24:27]
	v_mfma_f32_16x16x32_bf16 v[12:15], v[130:133], v[200:203], v[12:15]
	v_mfma_f32_16x16x32_bf16 v[8:11], v[138:141], v[200:203], v[8:11]
	v_mfma_f32_16x16x32_bf16 v[60:63], v[134:137], v[176:179], v[60:63]
	v_mfma_f32_16x16x32_bf16 v[56:59], v[142:145], v[176:179], v[56:59]
	v_mfma_f32_16x16x32_bf16 v[44:47], v[134:137], v[186:189], v[44:47]
	v_mfma_f32_16x16x32_bf16 v[40:43], v[142:145], v[186:189], v[40:43]
	v_mfma_f32_16x16x32_bf16 v[28:31], v[134:137], v[196:199], v[28:31]
	v_mfma_f32_16x16x32_bf16 v[24:27], v[142:145], v[196:199], v[24:27]
	v_mfma_f32_16x16x32_bf16 v[12:15], v[134:137], v[204:207], v[12:15]
	v_mfma_f32_16x16x32_bf16 v[8:11], v[142:145], v[204:207], v[8:11]
	v_mfma_f32_16x16x32_bf16 v[52:55], v[156:159], v[172:175], v[52:55]
	v_mfma_f32_16x16x32_bf16 v[48:51], v[164:167], v[172:175], v[48:51]
	v_mfma_f32_16x16x32_bf16 v[36:39], v[156:159], v[180:183], v[36:39]
	v_mfma_f32_16x16x32_bf16 v[32:35], v[164:167], v[180:183], v[32:35]
	v_mfma_f32_16x16x32_bf16 v[20:23], v[156:159], v[192:195], v[20:23]
	v_mfma_f32_16x16x32_bf16 v[16:19], v[164:167], v[192:195], v[16:19]
	v_mfma_f32_16x16x32_bf16 v[4:7], v[156:159], v[200:203], v[4:7]
	v_mfma_f32_16x16x32_bf16 v[0:3], v[164:167], v[200:203], v[0:3]
	v_mfma_f32_16x16x32_bf16 v[52:55], v[160:163], v[176:179], v[52:55]
	v_mfma_f32_16x16x32_bf16 v[48:51], v[168:171], v[176:179], v[48:51]
	v_mfma_f32_16x16x32_bf16 v[36:39], v[160:163], v[186:189], v[36:39]
	v_mfma_f32_16x16x32_bf16 v[32:35], v[168:171], v[186:189], v[32:35]
	v_mfma_f32_16x16x32_bf16 v[20:23], v[160:163], v[196:199], v[20:23]
	v_mfma_f32_16x16x32_bf16 v[16:19], v[168:171], v[196:199], v[16:19]
	v_mfma_f32_16x16x32_bf16 v[4:7], v[160:163], v[204:207], v[4:7]
	v_mfma_f32_16x16x32_bf16 v[0:3], v[168:171], v[204:207], v[0:3]
	s_barrier
	s_add_i32 s8, 0, 0x18000
	s_add_i32 s84, 0, 0x1c000
	v_add_u32_e32 v142, s8, v185
	v_add_u32_e32 v168, s84, v185
	ds_read_b128 v[130:133], v142
	ds_read_b128 v[134:137], v142 offset:1024
	ds_read_b128 v[138:141], v142 offset:2048
	ds_read_b128 v[142:145], v142 offset:3072
	ds_read_b128 v[156:159], v168
	ds_read_b128 v[160:163], v168 offset:1024
	ds_read_b128 v[164:167], v168 offset:2048
	ds_read_b128 v[168:171], v168 offset:3072
	s_add_u32 s64, s64, 0xb0000
	s_addc_u32 s65, s65, 0
	s_mov_b32 m0, s19
	v_lshl_add_u64 v[228:229], s[64:65], 0, v[150:151]
	ds_read_b128 v[172:175], v191 offset:32768
	ds_read_b128 v[176:179], v191 offset:33792
	ds_read_b128 v[180:183], v191 offset:34816
	ds_read_b128 v[186:189], v191 offset:35840
	ds_read_b128 v[192:195], v191 offset:36864
	ds_read_b128 v[196:199], v191 offset:37888
	ds_read_b128 v[200:203], v191 offset:38912
	ds_read_b128 v[204:207], v191 offset:39936
	global_load_lds_dwordx4 v[228:229], off
	v_lshl_add_u64 v[228:229], s[64:65], 0, v[148:149]
	s_mov_b32 m0, s20
	s_nop 0
	global_load_lds_dwordx4 v[228:229], off
	s_waitcnt vmcnt(8)
	s_waitcnt lgkmcnt(0)
	s_barrier
	v_mfma_f32_16x16x32_bf16 v[124:127], v[130:133], v[172:175], v[124:127]
	v_mfma_f32_16x16x32_bf16 v[120:123], v[138:141], v[172:175], v[120:123]
	v_mfma_f32_16x16x32_bf16 v[108:111], v[130:133], v[180:183], v[108:111]
	v_mfma_f32_16x16x32_bf16 v[104:107], v[138:141], v[180:183], v[104:107]
	v_mfma_f32_16x16x32_bf16 v[92:95], v[130:133], v[192:195], v[92:95]
	v_mfma_f32_16x16x32_bf16 v[88:91], v[138:141], v[192:195], v[88:91]
	v_mfma_f32_16x16x32_bf16 v[76:79], v[130:133], v[200:203], v[76:79]
	v_mfma_f32_16x16x32_bf16 v[72:75], v[138:141], v[200:203], v[72:75]
	v_mfma_f32_16x16x32_bf16 v[124:127], v[134:137], v[176:179], v[124:127]
	v_mfma_f32_16x16x32_bf16 v[120:123], v[142:145], v[176:179], v[120:123]
	v_mfma_f32_16x16x32_bf16 v[108:111], v[134:137], v[186:189], v[108:111]
	v_mfma_f32_16x16x32_bf16 v[104:107], v[142:145], v[186:189], v[104:107]
	v_mfma_f32_16x16x32_bf16 v[92:95], v[134:137], v[196:199], v[92:95]
	v_mfma_f32_16x16x32_bf16 v[88:91], v[142:145], v[196:199], v[88:91]
	v_mfma_f32_16x16x32_bf16 v[76:79], v[134:137], v[204:207], v[76:79]
	v_mfma_f32_16x16x32_bf16 v[72:75], v[142:145], v[204:207], v[72:75]
	v_mfma_f32_16x16x32_bf16 v[116:119], v[156:159], v[172:175], v[116:119]
	v_mfma_f32_16x16x32_bf16 v[112:115], v[164:167], v[172:175], v[112:115]
	v_mfma_f32_16x16x32_bf16 v[100:103], v[156:159], v[180:183], v[100:103]
	v_mfma_f32_16x16x32_bf16 v[96:99], v[164:167], v[180:183], v[96:99]
	v_mfma_f32_16x16x32_bf16 v[84:87], v[156:159], v[192:195], v[84:87]
	v_mfma_f32_16x16x32_bf16 v[80:83], v[164:167], v[192:195], v[80:83]
	v_mfma_f32_16x16x32_bf16 v[68:71], v[156:159], v[200:203], v[68:71]
	v_mfma_f32_16x16x32_bf16 v[64:67], v[164:167], v[200:203], v[64:67]
	v_mfma_f32_16x16x32_bf16 v[116:119], v[160:163], v[176:179], v[116:119]
	v_mfma_f32_16x16x32_bf16 v[112:115], v[168:171], v[176:179], v[112:115]
	v_mfma_f32_16x16x32_bf16 v[100:103], v[160:163], v[186:189], v[100:103]
	v_mfma_f32_16x16x32_bf16 v[96:99], v[168:171], v[186:189], v[96:99]
	v_mfma_f32_16x16x32_bf16 v[84:87], v[160:163], v[196:199], v[84:87]
	v_mfma_f32_16x16x32_bf16 v[80:83], v[168:171], v[196:199], v[80:83]
	v_mfma_f32_16x16x32_bf16 v[68:71], v[160:163], v[204:207], v[68:71]
	v_mfma_f32_16x16x32_bf16 v[64:67], v[168:171], v[204:207], v[64:67]
	s_barrier
; #define PG8_STAGE(bufoff, gbase, voff) do { _Pragma("unroll") for (int _i = 0; _i < 2; ++_i) \
;         __builtin_amdgcn_global_load_lds((const unsigned*)((const char*)(gbase) + (voff)[_i]), (PG8_LAS unsigned*)(lds + (bufoff) + ldsw + _i * 8192), 16, 0, 0); } while (0)
; #define PG8_LDA(dst, b, h) do { _Pragma("unroll") for (int m = 0; m < 4; ++m) _Pragma("unroll") for (int k = 0; k < 2; ++k) dst[m][k] = *(const PG8_LAS bf16x8*)(lds + PG8_SA(b, h) + aoff + m * 2048 + k * 1024); } while (0)
; #define PG8_MMA(ai, bj, At, Bt) do { __builtin_amdgcn_s_setprio(1); _Pragma("unroll") for (int m = 0; m < 4; ++m) _Pragma("unroll") for (int n = 0; n < 2; ++n) _Pragma("unroll") for (int k = 0; k < 2; ++k) \
;         acc[ai][bj][m][n] = __builtin_amdgcn_mfma_f32_16x16x32_bf16(Bt[n][k], At[m][k], acc[ai][bj][m][n], 0, 0, 0); __builtin_amdgcn_s_setprio(0); } while (0)
; #define PG8_WAIT_V(n) asm volatile("s_waitcnt vmcnt(" #n ")" ::: "memory")
; #define PG8_WAIT_L(n) asm volatile("s_waitcnt lgkmcnt(" #n ")" ::: "memory")
; #define PG8_BAR __builtin_amdgcn_s_barrier()
; #define PG8_SCHED __builtin_amdgcn_sched_barrier(0)
; template <class Epi, class Sched, bool ALIGN_EPI = false, bool SP2 = false>
; __device__ __forceinline__ void gemm_phase(PG8_LAS unsigned char* lds, const Gemm g, const Sched& S, const Epi& E) {
;     ...
;             PG8_LDA(At, 1, 1); PG8_STAGE(PG8_SB(1, 0), b3, voffB); PG8_STAGE(PG8_SB(1, 1), b3 + hstep, voffB); PG8_STAGE(PG8_SA(1, 0), a3, voffA);
;             PG8_WAIT_V(8); PG8_WAIT_L(0); PG8_BAR; PG8_MMA(1, 0, At, B0); PG8_MMA(1, 1, At, B1); PG8_BAR; PG8_SCHED;
;     ...
;         }
;         if constexpr (ALIGN_EPI) { if (wr == 0) PG8_BAR; }
	s_add_i32 s8, s8, s14
	v_lshl_add_u64 v[208:209], v[208:209], 0, s[90:91]
	s_mov_b32 m0, s8
	ds_read_b128 v[172:175], v191 offset:49152
	ds_read_b128 v[176:179], v191 offset:50176
	ds_read_b128 v[180:183], v191 offset:51200
	ds_read_b128 v[186:189], v191 offset:52224
	ds_read_b128 v[192:195], v191 offset:53248
	ds_read_b128 v[196:199], v191 offset:54272
	ds_read_b128 v[200:203], v191 offset:55296
	ds_read_b128 v[204:207], v191 offset:56320
	global_load_lds_dwordx4 v[208:209], off
	s_add_i32 m0, s8, 0x2000
	s_add_u32 s46, s46, 0xb0080
	v_lshl_add_u64 v[208:209], v[210:211], 0, s[90:91]
	s_addc_u32 s47, s47, 0
	s_add_i32 s8, s84, s14
	global_load_lds_dwordx4 v[208:209], off
	v_lshl_add_u64 v[208:209], s[46:47], 0, v[128:129]
	s_mov_b32 m0, s8
	s_nop 0
	global_load_lds_dwordx4 v[208:209], off
	v_lshl_add_u64 v[208:209], s[46:47], 0, v[146:147]
	s_add_i32 m0, s8, 0x2000
	s_nop 0
	global_load_lds_dwordx4 v[208:209], off
	v_lshl_add_u64 v[208:209], v[214:215], 0, s[90:91]
	s_mov_b32 m0, s27
	s_nop 0
	global_load_lds_dwordx4 v[208:209], off
	v_lshl_add_u64 v[208:209], v[222:223], 0, s[90:91]
	s_mov_b32 m0, s28
	s_nop 0
	global_load_lds_dwordx4 v[208:209], off
	s_waitcnt vmcnt(8)
	s_waitcnt lgkmcnt(0)
	s_barrier
	v_mfma_f32_16x16x32_bf16 v[60:63], v[130:133], v[172:175], v[60:63]
	v_mfma_f32_16x16x32_bf16 v[56:59], v[138:141], v[172:175], v[56:59]
	v_mfma_f32_16x16x32_bf16 v[44:47], v[130:133], v[180:183], v[44:47]
	v_mfma_f32_16x16x32_bf16 v[40:43], v[138:141], v[180:183], v[40:43]
	v_mfma_f32_16x16x32_bf16 v[28:31], v[130:133], v[192:195], v[28:31]
	v_mfma_f32_16x16x32_bf16 v[24:27], v[138:141], v[192:195], v[24:27]
	v_mfma_f32_16x16x32_bf16 v[12:15], v[130:133], v[200:203], v[12:15]
	v_mfma_f32_16x16x32_bf16 v[8:11], v[138:141], v[200:203], v[8:11]
	v_mfma_f32_16x16x32_bf16 v[60:63], v[134:137], v[176:179], v[60:63]
	v_mfma_f32_16x16x32_bf16 v[56:59], v[142:145], v[176:179], v[56:59]
	v_mfma_f32_16x16x32_bf16 v[44:47], v[134:137], v[186:189], v[44:47]
	v_mfma_f32_16x16x32_bf16 v[40:43], v[142:145], v[186:189], v[40:43]
	v_mfma_f32_16x16x32_bf16 v[28:31], v[134:137], v[196:199], v[28:31]
	v_mfma_f32_16x16x32_bf16 v[24:27], v[142:145], v[196:199], v[24:27]
	v_mfma_f32_16x16x32_bf16 v[12:15], v[134:137], v[204:207], v[12:15]
	v_mfma_f32_16x16x32_bf16 v[8:11], v[142:145], v[204:207], v[8:11]
	v_mfma_f32_16x16x32_bf16 v[52:55], v[156:159], v[172:175], v[52:55]
	v_mfma_f32_16x16x32_bf16 v[48:51], v[164:167], v[172:175], v[48:51]
	v_mfma_f32_16x16x32_bf16 v[36:39], v[156:159], v[180:183], v[36:39]
	v_mfma_f32_16x16x32_bf16 v[32:35], v[164:167], v[180:183], v[32:35]
	v_mfma_f32_16x16x32_bf16 v[20:23], v[156:159], v[192:195], v[20:23]
	v_mfma_f32_16x16x32_bf16 v[16:19], v[164:167], v[192:195], v[16:19]
	v_mfma_f32_16x16x32_bf16 v[4:7], v[156:159], v[200:203], v[4:7]
	v_mfma_f32_16x16x32_bf16 v[0:3], v[164:167], v[200:203], v[0:3]
	v_mfma_f32_16x16x32_bf16 v[52:55], v[160:163], v[176:179], v[52:55]
	v_mfma_f32_16x16x32_bf16 v[48:51], v[168:171], v[176:179], v[48:51]
	v_mfma_f32_16x16x32_bf16 v[36:39], v[160:163], v[186:189], v[36:39]
	v_mfma_f32_16x16x32_bf16 v[32:35], v[168:171], v[186:189], v[32:35]
	v_mfma_f32_16x16x32_bf16 v[20:23], v[160:163], v[196:199], v[20:23]
	v_mfma_f32_16x16x32_bf16 v[16:19], v[168:171], v[196:199], v[16:19]
	v_mfma_f32_16x16x32_bf16 v[4:7], v[160:163], v[204:207], v[4:7]
	v_mfma_f32_16x16x32_bf16 v[0:3], v[168:171], v[204:207], v[0:3]
	s_barrier
	s_add_i32 s70, s70, 2
	s_add_u32 s36, s36, 0x100
	s_addc_u32 s37, s37, 0
	s_cmp_gt_u32 s70, 41
	s_mov_b64 s[96:97], s[44:45]
	s_cbranch_scc0 .LBB0_957
	s_and_b64 vcc, exec, s[58:59]
	s_cbranch_vccz .LBB0_960
	s_barrier

; #define PG8_STAGE(bufoff, gbase, voff) do { _Pragma("unroll") for (int _i = 0; _i < 2; ++_i) \
;         __builtin_amdgcn_global_load_lds((const unsigned*)((const char*)(gbase) + (voff)[_i]), (PG8_LAS unsigned*)(lds + (bufoff) + ldsw + _i * 8192), 16, 0, 0); } while (0)
; #define PG8_LDA(dst, b, h) do { _Pragma("unroll") for (int m = 0; m < 4; ++m) _Pragma("unroll") for (int k = 0; k < 2; ++k) dst[m][k] = *(const PG8_LAS bf16x8*)(lds + PG8_SA(b, h) + aoff + m * 2048 + k * 1024); } while (0)
; #define PG8_LDB(dst, b, h) do { _Pragma("unroll") for (int n = 0; n < 2; ++n) _Pragma("unroll") for (int k = 0; k < 2; ++k) dst[n][k] = *(const PG8_LAS bf16x8*)(lds + PG8_SB(b, h) + boff + n * 2048 + k * 1024); } while (0)
; #define PG8_MMA(ai, bj, At, Bt) do { __builtin_amdgcn_s_setprio(1); _Pragma("unroll") for (int m = 0; m < 4; ++m) _Pragma("unroll") for (int n = 0; n < 2; ++n) _Pragma("unroll") for (int k = 0; k < 2; ++k) \
;         acc[ai][bj][m][n] = __builtin_amdgcn_mfma_f32_16x16x32_bf16(Bt[n][k], At[m][k], acc[ai][bj][m][n], 0, 0, 0); __builtin_amdgcn_s_setprio(0); } while (0)
; #define PG8_WAIT_V(n) asm volatile("s_waitcnt vmcnt(" #n ")" ::: "memory")
; template <class Epi, class Sched, bool ALIGN_EPI = false, bool SP2 = false>
; __device__ __forceinline__ void gemm_phase(PG8_LAS unsigned char* lds, const Gemm g, const Sched& S, const Epi& E) {
;     ...
;         const char* nA = has_next ? (const char*)g.A + (size_t)nxt.pm * tstep : cA; const char* nB = has_next ? (const char*)g.Bt + (size_t)nxt.pn * tstep : cB;
;         for (int t = 0; t < nt; t += 2) {
;             const bool last = (t == nt - 2);
;             const char* a1 = cA + (size_t)(t + 1) * kstep;
;             const char* a2 = last ? nA : cA + (size_t)(t + 2) * kstep; const char* b2 = last ? nB : cB + (size_t)(t + 2) * kstep;
;             const char* a3 = a2 + kstep; const char* b3 = b2 + kstep;
;             if (last && has_next) S.a_ready(nxt);
;             if constexpr (SP2) {
;             PG8_LDB(B0, 0, 0); PG8_LDB(B1, 0, 1); PG8_SCHED; PG8_LDA(At, 0, 0); PG8_STAGE(PG8_SA(1, 1), a1 + hstep, voffA);
;             PG8_WAIT_V(8); PG8_WAIT_L(0); PG8_BAR; PG8_MMA(0, 0, At, B0); PG8_MMA(0, 1, At, B1); PG8_BAR; PG8_SCHED;
;             PG8_LDA(At, 0, 1); PG8_STAGE(PG8_SB(0, 0), b2, voffB); PG8_STAGE(PG8_SB(0, 1), b2 + hstep, voffB); PG8_STAGE(PG8_SA(0, 0), a2, voffA);
.LBB0_995:
	s_add_u32 s42, s96, 0x100
	s_addc_u32 s43, s97, 0
	s_add_i32 s8, 0, 0x10000
	s_cmp_eq_u32 s84, 40
	s_cselect_b32 s65, s67, s43
	s_cselect_b32 s64, s66, s42
	s_cselect_b32 s47, s73, s37
	s_cselect_b32 s46, s72, s36
	s_add_i32 s85, 0, 0x14000
	v_add_u32_e32 v142, s8, v201
	v_add_u32_e32 v168, s85, v201
	ds_read_b128 v[130:133], v142
	ds_read_b128 v[134:137], v142 offset:1024
	ds_read_b128 v[138:141], v142 offset:2048
	ds_read_b128 v[142:145], v142 offset:3072
	ds_read_b128 v[156:159], v168
	ds_read_b128 v[160:163], v168 offset:1024
	ds_read_b128 v[164:167], v168 offset:2048
	ds_read_b128 v[168:171], v168 offset:3072
	v_lshl_add_u64 v[208:209], s[96:97], 0, v[152:153]
	s_add_i32 m0, s15, 0xc000
	ds_read_b128 v[172:175], v203
	ds_read_b128 v[176:179], v203 offset:1024
	ds_read_b128 v[180:183], v203 offset:2048
	ds_read_b128 v[184:187], v203 offset:3072
	ds_read_b128 v[188:191], v203 offset:4096
	ds_read_b128 v[192:195], v203 offset:5120
	ds_read_b128 v[196:199], v203 offset:6144
	ds_read_b128 v[204:207], v203 offset:7168
	global_load_lds_dwordx4 v[208:209], off
	v_lshl_add_u64 v[208:209], s[96:97], 0, v[154:155]
	s_add_i32 m0, s15, 0xe000
	s_nop 0
	global_load_lds_dwordx4 v[208:209], off
	s_waitcnt vmcnt(8)
	s_waitcnt lgkmcnt(0)
	s_barrier
	v_mfma_f32_16x16x32_bf16 v[124:127], v[130:133], v[172:175], v[124:127]
	v_mfma_f32_16x16x32_bf16 v[120:123], v[138:141], v[172:175], v[120:123]
	v_mfma_f32_16x16x32_bf16 v[108:111], v[130:133], v[180:183], v[108:111]
	v_mfma_f32_16x16x32_bf16 v[104:107], v[138:141], v[180:183], v[104:107]
	v_mfma_f32_16x16x32_bf16 v[92:95], v[130:133], v[188:191], v[92:95]
	v_mfma_f32_16x16x32_bf16 v[88:91], v[138:141], v[188:191], v[88:91]
	v_mfma_f32_16x16x32_bf16 v[76:79], v[130:133], v[196:199], v[76:79]
	v_mfma_f32_16x16x32_bf16 v[72:75], v[138:141], v[196:199], v[72:75]
	v_mfma_f32_16x16x32_bf16 v[124:127], v[134:137], v[176:179], v[124:127]
	v_mfma_f32_16x16x32_bf16 v[120:123], v[142:145], v[176:179], v[120:123]
	v_mfma_f32_16x16x32_bf16 v[108:111], v[134:137], v[184:187], v[108:111]
	v_mfma_f32_16x16x32_bf16 v[104:107], v[142:145], v[184:187], v[104:107]
	v_mfma_f32_16x16x32_bf16 v[92:95], v[134:137], v[192:195], v[92:95]
	v_mfma_f32_16x16x32_bf16 v[88:91], v[142:145], v[192:195], v[88:91]
	v_mfma_f32_16x16x32_bf16 v[76:79], v[134:137], v[204:207], v[76:79]
	v_mfma_f32_16x16x32_bf16 v[72:75], v[142:145], v[204:207], v[72:75]
	v_mfma_f32_16x16x32_bf16 v[116:119], v[156:159], v[172:175], v[116:119]
	v_mfma_f32_16x16x32_bf16 v[112:115], v[164:167], v[172:175], v[112:115]
	v_mfma_f32_16x16x32_bf16 v[100:103], v[156:159], v[180:183], v[100:103]
	v_mfma_f32_16x16x32_bf16 v[96:99], v[164:167], v[180:183], v[96:99]
	v_mfma_f32_16x16x32_bf16 v[84:87], v[156:159], v[188:191], v[84:87]
	v_mfma_f32_16x16x32_bf16 v[80:83], v[164:167], v[188:191], v[80:83]
	v_mfma_f32_16x16x32_bf16 v[68:71], v[156:159], v[196:199], v[68:71]
	v_mfma_f32_16x16x32_bf16 v[64:67], v[164:167], v[196:199], v[64:67]
	v_mfma_f32_16x16x32_bf16 v[116:119], v[160:163], v[176:179], v[116:119]
	v_mfma_f32_16x16x32_bf16 v[112:115], v[168:171], v[176:179], v[112:115]
	v_mfma_f32_16x16x32_bf16 v[100:103], v[160:163], v[184:187], v[100:103]
	v_mfma_f32_16x16x32_bf16 v[96:99], v[168:171], v[184:187], v[96:99]
	v_mfma_f32_16x16x32_bf16 v[84:87], v[160:163], v[192:195], v[84:87]
	v_mfma_f32_16x16x32_bf16 v[80:83], v[168:171], v[192:195], v[80:83]
	v_mfma_f32_16x16x32_bf16 v[68:71], v[160:163], v[204:207], v[68:71]
	v_mfma_f32_16x16x32_bf16 v[64:67], v[168:171], v[204:207], v[64:67]
	s_barrier
	s_add_i32 s8, s8, s14
	v_lshl_add_u64 v[208:209], s[46:47], 0, v[128:129]
	s_mov_b32 m0, s8
	ds_read_b128 v[172:175], v203 offset:16384
	ds_read_b128 v[176:179], v203 offset:17408
	ds_read_b128 v[180:183], v203 offset:18432
	ds_read_b128 v[184:187], v203 offset:19456
	ds_read_b128 v[188:191], v203 offset:20480
	ds_read_b128 v[192:195], v203 offset:21504
	ds_read_b128 v[196:199], v203 offset:22528
	ds_read_b128 v[204:207], v203 offset:23552
	global_load_lds_dwordx4 v[208:209], off
	s_add_i32 m0, s8, 0x2000
	s_add_u32 s96, s46, 0xb0000
	v_lshl_add_u64 v[210:211], s[46:47], 0, v[146:147]
	s_addc_u32 s97, s47, 0
	s_add_i32 s8, s85, s14
	global_load_lds_dwordx4 v[210:211], off
	v_lshl_add_u64 v[214:215], s[96:97], 0, v[128:129]
	s_mov_b32 m0, s8
	v_lshl_add_u64 v[222:223], s[64:65], 0, v[148:149]
	global_load_lds_dwordx4 v[214:215], off
	v_lshl_add_u64 v[214:215], s[96:97], 0, v[146:147]
	s_add_i32 m0, s8, 0x2000
	s_nop 0
	global_load_lds_dwordx4 v[214:215], off
	v_lshl_add_u64 v[214:215], s[64:65], 0, v[150:151]
	s_mov_b32 m0, s15
	s_nop 0
	global_load_lds_dwordx4 v[214:215], off
	s_mov_b32 m0, s18
	s_nop 0
	global_load_lds_dwordx4 v[222:223], off
	s_waitcnt vmcnt(8)
	s_waitcnt lgkmcnt(0)
	s_barrier
; #define PG8_STAGE(bufoff, gbase, voff) do { _Pragma("unroll") for (int _i = 0; _i < 2; ++_i) \
;         __builtin_amdgcn_global_load_lds((const unsigned*)((const char*)(gbase) + (voff)[_i]), (PG8_LAS unsigned*)(lds + (bufoff) + ldsw + _i * 8192), 16, 0, 0); } while (0)
; #define PG8_LDA(dst, b, h) do { _Pragma("unroll") for (int m = 0; m < 4; ++m) _Pragma("unroll") for (int k = 0; k < 2; ++k) dst[m][k] = *(const PG8_LAS bf16x8*)(lds + PG8_SA(b, h) + aoff + m * 2048 + k * 1024); } while (0)
; #define PG8_LDB(dst, b, h) do { _Pragma("unroll") for (int n = 0; n < 2; ++n) _Pragma("unroll") for (int k = 0; k < 2; ++k) dst[n][k] = *(const PG8_LAS bf16x8*)(lds + PG8_SB(b, h) + boff + n * 2048 + k * 1024); } while (0)
; #define PG8_MMA(ai, bj, At, Bt) do { __builtin_amdgcn_s_setprio(1); _Pragma("unroll") for (int m = 0; m < 4; ++m) _Pragma("unroll") for (int n = 0; n < 2; ++n) _Pragma("unroll") for (int k = 0; k < 2; ++k) \
;         acc[ai][bj][m][n] = __builtin_amdgcn_mfma_f32_16x16x32_bf16(Bt[n][k], At[m][k], acc[ai][bj][m][n], 0, 0, 0); __builtin_amdgcn_s_setprio(0); } while (0)
; #define PG8_WAIT_V(n) asm volatile("s_waitcnt vmcnt(" #n ")" ::: "memory")
; #define PG8_WAIT_L(n) asm volatile("s_waitcnt lgkmcnt(" #n ")" ::: "memory")
; #define PG8_BAR __builtin_amdgcn_s_barrier()
; #define PG8_SCHED __builtin_amdgcn_sched_barrier(0)
; template <class Epi, class Sched, bool ALIGN_EPI = false, bool SP2 = false>
; __device__ __forceinline__ void gemm_phase(PG8_LAS unsigned char* lds, const Gemm g, const Sched& S, const Epi& E) {
;     ...
;             PG8_WAIT_V(8); PG8_WAIT_L(0); PG8_BAR; PG8_MMA(1, 0, At, B0); PG8_MMA(1, 1, At, B1); PG8_BAR; PG8_SCHED;
;             PG8_LDB(B0, 1, 0); PG8_LDB(B1, 1, 1); PG8_SCHED; PG8_LDA(At, 1, 0); PG8_STAGE(PG8_SA(0, 1), a2 + hstep, voffA);
;             PG8_WAIT_V(8); PG8_WAIT_L(0); PG8_BAR; PG8_MMA(0, 0, At, B0); PG8_MMA(0, 1, At, B1); PG8_BAR; PG8_SCHED;
	v_mfma_f32_16x16x32_bf16 v[60:63], v[130:133], v[172:175], v[60:63]
	v_mfma_f32_16x16x32_bf16 v[56:59], v[138:141], v[172:175], v[56:59]
	v_mfma_f32_16x16x32_bf16 v[44:47], v[130:133], v[180:183], v[44:47]
	v_mfma_f32_16x16x32_bf16 v[40:43], v[138:141], v[180:183], v[40:43]
	v_mfma_f32_16x16x32_bf16 v[28:31], v[130:133], v[188:191], v[28:31]
	v_mfma_f32_16x16x32_bf16 v[24:27], v[138:141], v[188:191], v[24:27]
	v_mfma_f32_16x16x32_bf16 v[12:15], v[130:133], v[196:199], v[12:15]
	v_mfma_f32_16x16x32_bf16 v[8:11], v[138:141], v[196:199], v[8:11]
	v_mfma_f32_16x16x32_bf16 v[60:63], v[134:137], v[176:179], v[60:63]
	v_mfma_f32_16x16x32_bf16 v[56:59], v[142:145], v[176:179], v[56:59]
	v_mfma_f32_16x16x32_bf16 v[44:47], v[134:137], v[184:187], v[44:47]
	v_mfma_f32_16x16x32_bf16 v[40:43], v[142:145], v[184:187], v[40:43]
	v_mfma_f32_16x16x32_bf16 v[28:31], v[134:137], v[192:195], v[28:31]
	v_mfma_f32_16x16x32_bf16 v[24:27], v[142:145], v[192:195], v[24:27]
	v_mfma_f32_16x16x32_bf16 v[12:15], v[134:137], v[204:207], v[12:15]
	v_mfma_f32_16x16x32_bf16 v[8:11], v[142:145], v[204:207], v[8:11]
	v_mfma_f32_16x16x32_bf16 v[52:55], v[156:159], v[172:175], v[52:55]
	v_mfma_f32_16x16x32_bf16 v[48:51], v[164:167], v[172:175], v[48:51]
	v_mfma_f32_16x16x32_bf16 v[36:39], v[156:159], v[180:183], v[36:39]
	v_mfma_f32_16x16x32_bf16 v[32:35], v[164:167], v[180:183], v[32:35]
	v_mfma_f32_16x16x32_bf16 v[20:23], v[156:159], v[188:191], v[20:23]
	v_mfma_f32_16x16x32_bf16 v[16:19], v[164:167], v[188:191], v[16:19]
	v_mfma_f32_16x16x32_bf16 v[4:7], v[156:159], v[196:199], v[4:7]
	v_mfma_f32_16x16x32_bf16 v[0:3], v[164:167], v[196:199], v[0:3]
	v_mfma_f32_16x16x32_bf16 v[52:55], v[160:163], v[176:179], v[52:55]
	v_mfma_f32_16x16x32_bf16 v[48:51], v[168:171], v[176:179], v[48:51]
	v_mfma_f32_16x16x32_bf16 v[36:39], v[160:163], v[184:187], v[36:39]
	v_mfma_f32_16x16x32_bf16 v[32:35], v[168:171], v[184:187], v[32:35]
	v_mfma_f32_16x16x32_bf16 v[20:23], v[160:163], v[192:195], v[20:23]
	v_mfma_f32_16x16x32_bf16 v[16:19], v[168:171], v[192:195], v[16:19]
	v_mfma_f32_16x16x32_bf16 v[4:7], v[160:163], v[204:207], v[4:7]
	v_mfma_f32_16x16x32_bf16 v[0:3], v[168:171], v[204:207], v[0:3]
	s_barrier
	s_add_i32 s8, 0, 0x18000
	s_add_i32 s85, 0, 0x1c000
	v_add_u32_e32 v142, s8, v201
	v_add_u32_e32 v168, s85, v201
	ds_read_b128 v[130:133], v142
	ds_read_b128 v[134:137], v142 offset:1024
	ds_read_b128 v[138:141], v142 offset:2048
	ds_read_b128 v[142:145], v142 offset:3072
	ds_read_b128 v[156:159], v168
	ds_read_b128 v[160:163], v168 offset:1024
	ds_read_b128 v[164:167], v168 offset:2048
	ds_read_b128 v[168:171], v168 offset:3072
	s_add_u32 s64, s64, 0xb0000
	s_addc_u32 s65, s65, 0
	s_mov_b32 m0, s19
	v_lshl_add_u64 v[228:229], s[64:65], 0, v[150:151]
	ds_read_b128 v[172:175], v203 offset:32768
	ds_read_b128 v[176:179], v203 offset:33792
	ds_read_b128 v[180:183], v203 offset:34816
	ds_read_b128 v[184:187], v203 offset:35840
	ds_read_b128 v[188:191], v203 offset:36864
	ds_read_b128 v[192:195], v203 offset:37888
	ds_read_b128 v[196:199], v203 offset:38912
	ds_read_b128 v[204:207], v203 offset:39936
	global_load_lds_dwordx4 v[228:229], off
	v_lshl_add_u64 v[228:229], s[64:65], 0, v[148:149]
	s_mov_b32 m0, s20
	s_nop 0
	global_load_lds_dwordx4 v[228:229], off
	s_waitcnt vmcnt(8)
	s_waitcnt lgkmcnt(0)
	s_barrier
	v_mfma_f32_16x16x32_bf16 v[124:127], v[130:133], v[172:175], v[124:127]
	v_mfma_f32_16x16x32_bf16 v[120:123], v[138:141], v[172:175], v[120:123]
	v_mfma_f32_16x16x32_bf16 v[108:111], v[130:133], v[180:183], v[108:111]
	v_mfma_f32_16x16x32_bf16 v[104:107], v[138:141], v[180:183], v[104:107]
	v_mfma_f32_16x16x32_bf16 v[92:95], v[130:133], v[188:191], v[92:95]
	v_mfma_f32_16x16x32_bf16 v[88:91], v[138:141], v[188:191], v[88:91]
	v_mfma_f32_16x16x32_bf16 v[76:79], v[130:133], v[196:199], v[76:79]
	v_mfma_f32_16x16x32_bf16 v[72:75], v[138:141], v[196:199], v[72:75]
	v_mfma_f32_16x16x32_bf16 v[124:127], v[134:137], v[176:179], v[124:127]
	v_mfma_f32_16x16x32_bf16 v[120:123], v[142:145], v[176:179], v[120:123]
	v_mfma_f32_16x16x32_bf16 v[108:111], v[134:137], v[184:187], v[108:111]
	v_mfma_f32_16x16x32_bf16 v[104:107], v[142:145], v[184:187], v[104:107]
	v_mfma_f32_16x16x32_bf16 v[92:95], v[134:137], v[192:195], v[92:95]
	v_mfma_f32_16x16x32_bf16 v[88:91], v[142:145], v[192:195], v[88:91]
	v_mfma_f32_16x16x32_bf16 v[76:79], v[134:137], v[204:207], v[76:79]
	v_mfma_f32_16x16x32_bf16 v[72:75], v[142:145], v[204:207], v[72:75]
	v_mfma_f32_16x16x32_bf16 v[116:119], v[156:159], v[172:175], v[116:119]
	v_mfma_f32_16x16x32_bf16 v[112:115], v[164:167], v[172:175], v[112:115]
	v_mfma_f32_16x16x32_bf16 v[100:103], v[156:159], v[180:183], v[100:103]
	v_mfma_f32_16x16x32_bf16 v[96:99], v[164:167], v[180:183], v[96:99]
	v_mfma_f32_16x16x32_bf16 v[84:87], v[156:159], v[188:191], v[84:87]
	v_mfma_f32_16x16x32_bf16 v[80:83], v[164:167], v[188:191], v[80:83]
	v_mfma_f32_16x16x32_bf16 v[68:71], v[156:159], v[196:199], v[68:71]
	v_mfma_f32_16x16x32_bf16 v[64:67], v[164:167], v[196:199], v[64:67]
	v_mfma_f32_16x16x32_bf16 v[116:119], v[160:163], v[176:179], v[116:119]
	v_mfma_f32_16x16x32_bf16 v[112:115], v[168:171], v[176:179], v[112:115]
	v_mfma_f32_16x16x32_bf16 v[100:103], v[160:163], v[184:187], v[100:103]
	v_mfma_f32_16x16x32_bf16 v[96:99], v[168:171], v[184:187], v[96:99]
	v_mfma_f32_16x16x32_bf16 v[84:87], v[160:163], v[192:195], v[84:87]
	v_mfma_f32_16x16x32_bf16 v[80:83], v[168:171], v[192:195], v[80:83]
	v_mfma_f32_16x16x32_bf16 v[68:71], v[160:163], v[204:207], v[68:71]
	v_mfma_f32_16x16x32_bf16 v[64:67], v[168:171], v[204:207], v[64:67]
	s_barrier
; #define PG8_STAGE(bufoff, gbase, voff) do { _Pragma("unroll") for (int _i = 0; _i < 2; ++_i) \
;         __builtin_amdgcn_global_load_lds((const unsigned*)((const char*)(gbase) + (voff)[_i]), (PG8_LAS unsigned*)(lds + (bufoff) + ldsw + _i * 8192), 16, 0, 0); } while (0)
; #define PG8_LDA(dst, b, h) do { _Pragma("unroll") for (int m = 0; m < 4; ++m) _Pragma("unroll") for (int k = 0; k < 2; ++k) dst[m][k] = *(const PG8_LAS bf16x8*)(lds + PG8_SA(b, h) + aoff + m * 2048 + k * 1024); } while (0)
; #define PG8_MMA(ai, bj, At, Bt) do { __builtin_amdgcn_s_setprio(1); _Pragma("unroll") for (int m = 0; m < 4; ++m) _Pragma("unroll") for (int n = 0; n < 2; ++n) _Pragma("unroll") for (int k = 0; k < 2; ++k) \
;         acc[ai][bj][m][n] = __builtin_amdgcn_mfma_f32_16x16x32_bf16(Bt[n][k], At[m][k], acc[ai][bj][m][n], 0, 0, 0); __builtin_amdgcn_s_setprio(0); } while (0)
; #define PG8_WAIT_V(n) asm volatile("s_waitcnt vmcnt(" #n ")" ::: "memory")
; #define PG8_WAIT_L(n) asm volatile("s_waitcnt lgkmcnt(" #n ")" ::: "memory")
; #define PG8_BAR __builtin_amdgcn_s_barrier()
; #define PG8_SCHED __builtin_amdgcn_sched_barrier(0)
; template <class Epi, class Sched, bool ALIGN_EPI = false, bool SP2 = false>
; __device__ __forceinline__ void gemm_phase(PG8_LAS unsigned char* lds, const Gemm g, const Sched& S, const Epi& E) {
;     ...
;             PG8_LDA(At, 1, 1); PG8_STAGE(PG8_SB(1, 0), b3, voffB); PG8_STAGE(PG8_SB(1, 1), b3 + hstep, voffB); PG8_STAGE(PG8_SA(1, 0), a3, voffA);
;             PG8_WAIT_V(8); PG8_WAIT_L(0); PG8_BAR; PG8_MMA(1, 0, At, B0); PG8_MMA(1, 1, At, B1); PG8_BAR; PG8_SCHED;
;     ...
;         }
;         if constexpr (ALIGN_EPI) { if (wr == 0) PG8_BAR; }
	s_add_i32 s8, s8, s14
	v_lshl_add_u64 v[208:209], v[208:209], 0, s[90:91]
	s_mov_b32 m0, s8
	ds_read_b128 v[172:175], v203 offset:49152
	ds_read_b128 v[176:179], v203 offset:50176
	ds_read_b128 v[180:183], v203 offset:51200
	ds_read_b128 v[184:187], v203 offset:52224
	ds_read_b128 v[188:191], v203 offset:53248
	ds_read_b128 v[192:195], v203 offset:54272
	ds_read_b128 v[196:199], v203 offset:55296
	ds_read_b128 v[204:207], v203 offset:56320
	global_load_lds_dwordx4 v[208:209], off
	s_add_i32 m0, s8, 0x2000
	s_add_u32 s46, s46, 0xb0080
	v_lshl_add_u64 v[208:209], v[210:211], 0, s[90:91]
	s_addc_u32 s47, s47, 0
	s_add_i32 s8, s85, s14
	global_load_lds_dwordx4 v[208:209], off
	v_lshl_add_u64 v[208:209], s[46:47], 0, v[128:129]
	s_mov_b32 m0, s8
	s_nop 0
	global_load_lds_dwordx4 v[208:209], off
	v_lshl_add_u64 v[208:209], s[46:47], 0, v[146:147]
	s_add_i32 m0, s8, 0x2000
	s_nop 0
	global_load_lds_dwordx4 v[208:209], off
	v_lshl_add_u64 v[208:209], v[214:215], 0, s[90:91]
	s_mov_b32 m0, s29
	s_nop 0
	global_load_lds_dwordx4 v[208:209], off
	v_lshl_add_u64 v[208:209], v[222:223], 0, s[90:91]
	s_mov_b32 m0, s30
	s_nop 0
	global_load_lds_dwordx4 v[208:209], off
	s_waitcnt vmcnt(8)
	s_waitcnt lgkmcnt(0)
	s_barrier
	v_mfma_f32_16x16x32_bf16 v[60:63], v[130:133], v[172:175], v[60:63]
	v_mfma_f32_16x16x32_bf16 v[56:59], v[138:141], v[172:175], v[56:59]
	v_mfma_f32_16x16x32_bf16 v[44:47], v[130:133], v[180:183], v[44:47]
	v_mfma_f32_16x16x32_bf16 v[40:43], v[138:141], v[180:183], v[40:43]
	v_mfma_f32_16x16x32_bf16 v[28:31], v[130:133], v[188:191], v[28:31]
	v_mfma_f32_16x16x32_bf16 v[24:27], v[138:141], v[188:191], v[24:27]
	v_mfma_f32_16x16x32_bf16 v[12:15], v[130:133], v[196:199], v[12:15]
	v_mfma_f32_16x16x32_bf16 v[8:11], v[138:141], v[196:199], v[8:11]
	v_mfma_f32_16x16x32_bf16 v[60:63], v[134:137], v[176:179], v[60:63]
	v_mfma_f32_16x16x32_bf16 v[56:59], v[142:145], v[176:179], v[56:59]
	v_mfma_f32_16x16x32_bf16 v[44:47], v[134:137], v[184:187], v[44:47]
	v_mfma_f32_16x16x32_bf16 v[40:43], v[142:145], v[184:187], v[40:43]
	v_mfma_f32_16x16x32_bf16 v[28:31], v[134:137], v[192:195], v[28:31]
	v_mfma_f32_16x16x32_bf16 v[24:27], v[142:145], v[192:195], v[24:27]
	v_mfma_f32_16x16x32_bf16 v[12:15], v[134:137], v[204:207], v[12:15]
	v_mfma_f32_16x16x32_bf16 v[8:11], v[142:145], v[204:207], v[8:11]
	v_mfma_f32_16x16x32_bf16 v[52:55], v[156:159], v[172:175], v[52:55]
	v_mfma_f32_16x16x32_bf16 v[48:51], v[164:167], v[172:175], v[48:51]
	v_mfma_f32_16x16x32_bf16 v[36:39], v[156:159], v[180:183], v[36:39]
	v_mfma_f32_16x16x32_bf16 v[32:35], v[164:167], v[180:183], v[32:35]
	v_mfma_f32_16x16x32_bf16 v[20:23], v[156:159], v[188:191], v[20:23]
	v_mfma_f32_16x16x32_bf16 v[16:19], v[164:167], v[188:191], v[16:19]
	v_mfma_f32_16x16x32_bf16 v[4:7], v[156:159], v[196:199], v[4:7]
	v_mfma_f32_16x16x32_bf16 v[0:3], v[164:167], v[196:199], v[0:3]
	v_mfma_f32_16x16x32_bf16 v[52:55], v[160:163], v[176:179], v[52:55]
	v_mfma_f32_16x16x32_bf16 v[48:51], v[168:171], v[176:179], v[48:51]
	v_mfma_f32_16x16x32_bf16 v[36:39], v[160:163], v[184:187], v[36:39]
	v_mfma_f32_16x16x32_bf16 v[32:35], v[168:171], v[184:187], v[32:35]
	v_mfma_f32_16x16x32_bf16 v[20:23], v[160:163], v[192:195], v[20:23]
	v_mfma_f32_16x16x32_bf16 v[16:19], v[168:171], v[192:195], v[16:19]
	v_mfma_f32_16x16x32_bf16 v[4:7], v[160:163], v[204:207], v[4:7]
	v_mfma_f32_16x16x32_bf16 v[0:3], v[168:171], v[204:207], v[0:3]
	s_barrier
	s_add_i32 s84, s84, 2
	s_add_u32 s36, s36, 0x100
	s_addc_u32 s37, s37, 0
	s_cmp_gt_u32 s84, 41
	s_mov_b64 s[96:97], s[42:43]
	s_cbranch_scc0 .LBB0_995
	s_and_b64 vcc, exec, s[62:63]
	s_cbranch_vccz .LBB0_998
	s_barrier
